# v006 plus: GEMM K loops drop the back-to-back setprio 0/1 between the two MFMA blocks of a segment and lower the priority after the segment barrier instead of before it
# speedup vs baseline: 1.0200x; 1.0037x over previous
.LBB0_183:
	s_add_u32 s14, s4, 0xfffc0080
	s_addc_u32 s15, s5, -1
	s_add_i32 s53, 0, 0x10000
	s_cmp_eq_u32 s49, 12
	s_cselect_b32 s55, s21, s15
	s_cselect_b32 s54, s28, s14
	v_add_u32_e32 v142, s53, v147
	s_cselect_b32 s15, s29, s47
	s_cselect_b32 s14, s33, s37
	s_add_i32 s67, 0, 0x14000
	ds_read_b128 v[150:153], v142
	ds_read_b128 v[154:157], v142 offset:1024
	ds_read_b128 v[158:161], v142 offset:2048
	ds_read_b128 v[162:165], v142 offset:3072
	v_add_u32_e32 v142, s67, v147
	ds_read_b128 v[166:169], v142
	ds_read_b128 v[170:173], v142 offset:1024
	ds_read_b128 v[174:177], v142 offset:2048
	ds_read_b128 v[178:181], v142 offset:3072
	v_lshl_add_u64 v[144:145], s[4:5], 0, v[140:141]
	s_add_i32 m0, s59, 0xc000
	ds_read_b128 v[182:185], v149
	ds_read_b128 v[186:189], v149 offset:1024
	ds_read_b128 v[190:193], v149 offset:2048
	ds_read_b128 v[202:205], v149 offset:3072
	ds_read_b128 v[206:209], v149 offset:4096
	ds_read_b128 v[210:213], v149 offset:5120
	ds_read_b128 v[214:217], v149 offset:6144
	ds_read_b128 v[218:221], v149 offset:7168
	global_load_lds_dwordx4 v[144:145], off
	v_lshl_add_u64 v[144:145], s[4:5], 0, v[138:139]
	s_add_i32 m0, s59, 0xe000
	s_nop 0
	global_load_lds_dwordx4 v[144:145], off
	s_waitcnt vmcnt(8)
	s_waitcnt lgkmcnt(0)
	s_barrier
	s_setprio 1
	s_waitcnt lgkmcnt(0)
	v_mfma_f32_16x16x32_bf16 v[126:129], v[150:153], v[182:185], v[126:129]
	v_mfma_f32_16x16x32_bf16 v[122:125], v[158:161], v[182:185], v[122:125]
	v_mfma_f32_16x16x32_bf16 v[110:113], v[150:153], v[190:193], v[110:113]
	v_mfma_f32_16x16x32_bf16 v[106:109], v[158:161], v[190:193], v[106:109]
	v_mfma_f32_16x16x32_bf16 v[94:97], v[150:153], v[206:209], v[94:97]
	v_mfma_f32_16x16x32_bf16 v[90:93], v[158:161], v[206:209], v[90:93]
	v_mfma_f32_16x16x32_bf16 v[78:81], v[150:153], v[214:217], v[78:81]
	v_mfma_f32_16x16x32_bf16 v[74:77], v[158:161], v[214:217], v[74:77]
	v_mfma_f32_16x16x32_bf16 v[126:129], v[154:157], v[186:189], v[126:129]
	v_mfma_f32_16x16x32_bf16 v[122:125], v[162:165], v[186:189], v[122:125]
	v_mfma_f32_16x16x32_bf16 v[110:113], v[154:157], v[202:205], v[110:113]
	v_mfma_f32_16x16x32_bf16 v[106:109], v[162:165], v[202:205], v[106:109]
	v_mfma_f32_16x16x32_bf16 v[94:97], v[154:157], v[210:213], v[94:97]
	v_mfma_f32_16x16x32_bf16 v[90:93], v[162:165], v[210:213], v[90:93]
	v_mfma_f32_16x16x32_bf16 v[78:81], v[154:157], v[218:221], v[78:81]
	v_mfma_f32_16x16x32_bf16 v[74:77], v[162:165], v[218:221], v[74:77]
	v_mfma_f32_16x16x32_bf16 v[118:121], v[166:169], v[182:185], v[118:121]
	v_mfma_f32_16x16x32_bf16 v[114:117], v[174:177], v[182:185], v[114:117]
	v_mfma_f32_16x16x32_bf16 v[102:105], v[166:169], v[190:193], v[102:105]
	v_mfma_f32_16x16x32_bf16 v[98:101], v[174:177], v[190:193], v[98:101]
	v_mfma_f32_16x16x32_bf16 v[86:89], v[166:169], v[206:209], v[86:89]
	v_mfma_f32_16x16x32_bf16 v[82:85], v[174:177], v[206:209], v[82:85]
	v_mfma_f32_16x16x32_bf16 v[70:73], v[166:169], v[214:217], v[70:73]
	v_mfma_f32_16x16x32_bf16 v[66:69], v[174:177], v[214:217], v[66:69]
	v_mfma_f32_16x16x32_bf16 v[118:121], v[170:173], v[186:189], v[118:121]
	v_mfma_f32_16x16x32_bf16 v[114:117], v[178:181], v[186:189], v[114:117]
	v_mfma_f32_16x16x32_bf16 v[102:105], v[170:173], v[202:205], v[102:105]
	v_mfma_f32_16x16x32_bf16 v[98:101], v[178:181], v[202:205], v[98:101]
	v_mfma_f32_16x16x32_bf16 v[86:89], v[170:173], v[210:213], v[86:89]
	v_mfma_f32_16x16x32_bf16 v[82:85], v[178:181], v[210:213], v[82:85]
	v_mfma_f32_16x16x32_bf16 v[70:73], v[170:173], v[218:221], v[70:73]
	v_mfma_f32_16x16x32_bf16 v[66:69], v[178:181], v[218:221], v[66:69]
	s_barrier
	s_setprio 0
	s_add_i32 s53, s53, s58
	v_lshl_add_u64 v[144:145], s[14:15], 0, v[134:135]
	s_mov_b32 m0, s53
	ds_read_b128 v[182:185], v149 offset:16384
	ds_read_b128 v[186:189], v149 offset:17408
	ds_read_b128 v[190:193], v149 offset:18432
	ds_read_b128 v[202:205], v149 offset:19456
	ds_read_b128 v[206:209], v149 offset:20480
	ds_read_b128 v[210:213], v149 offset:21504
	ds_read_b128 v[214:217], v149 offset:22528
	ds_read_b128 v[218:221], v149 offset:23552
	global_load_lds_dwordx4 v[144:145], off
	s_add_i32 m0, s53, 0x2000
	s_add_u32 s68, s14, 0x40000
	v_lshl_add_u64 v[222:223], s[14:15], 0, v[130:131]
	s_addc_u32 s69, s15, 0
	s_add_i32 s53, s67, s58
	global_load_lds_dwordx4 v[222:223], off
	v_lshl_add_u64 v[232:233], s[68:69], 0, v[134:135]
	s_mov_b32 m0, s53
	v_lshl_add_u64 v[234:235], s[54:55], 0, v[132:133]
	global_load_lds_dwordx4 v[232:233], off
	v_lshl_add_u64 v[232:233], s[68:69], 0, v[130:131]
	s_add_i32 m0, s53, 0x2000
	s_nop 0
	global_load_lds_dwordx4 v[232:233], off
	v_lshl_add_u64 v[232:233], s[54:55], 0, v[136:137]
	s_mov_b32 m0, s59
	s_nop 0
	global_load_lds_dwordx4 v[232:233], off
	s_mov_b32 m0, s60
	s_nop 0
	global_load_lds_dwordx4 v[234:235], off
	s_waitcnt vmcnt(8)
	s_waitcnt lgkmcnt(0)
	s_barrier
	s_setprio 1
	s_waitcnt lgkmcnt(0)
	v_mfma_f32_16x16x32_bf16 v[62:65], v[150:153], v[182:185], v[62:65]
	v_mfma_f32_16x16x32_bf16 v[58:61], v[158:161], v[182:185], v[58:61]
	v_mfma_f32_16x16x32_bf16 v[50:53], v[150:153], v[190:193], v[50:53]
	v_mfma_f32_16x16x32_bf16 v[42:45], v[158:161], v[190:193], v[42:45]
	v_mfma_f32_16x16x32_bf16 v[34:37], v[150:153], v[206:209], v[34:37]
	v_mfma_f32_16x16x32_bf16 v[26:29], v[158:161], v[206:209], v[26:29]
	v_mfma_f32_16x16x32_bf16 v[18:21], v[150:153], v[214:217], v[18:21]
	v_mfma_f32_16x16x32_bf16 v[10:13], v[158:161], v[214:217], v[10:13]
	v_mfma_f32_16x16x32_bf16 v[62:65], v[154:157], v[186:189], v[62:65]
	v_mfma_f32_16x16x32_bf16 v[58:61], v[162:165], v[186:189], v[58:61]
	v_mfma_f32_16x16x32_bf16 v[50:53], v[154:157], v[202:205], v[50:53]
	v_mfma_f32_16x16x32_bf16 v[42:45], v[162:165], v[202:205], v[42:45]
	v_mfma_f32_16x16x32_bf16 v[34:37], v[154:157], v[210:213], v[34:37]
	v_mfma_f32_16x16x32_bf16 v[26:29], v[162:165], v[210:213], v[26:29]
	v_mfma_f32_16x16x32_bf16 v[18:21], v[154:157], v[218:221], v[18:21]
	v_mfma_f32_16x16x32_bf16 v[10:13], v[162:165], v[218:221], v[10:13]
	v_mfma_f32_16x16x32_bf16 v[54:57], v[166:169], v[182:185], v[54:57]
	v_mfma_f32_16x16x32_bf16 v[46:49], v[174:177], v[182:185], v[46:49]
	v_mfma_f32_16x16x32_bf16 v[38:41], v[166:169], v[190:193], v[38:41]
	v_mfma_f32_16x16x32_bf16 v[30:33], v[174:177], v[190:193], v[30:33]
	v_mfma_f32_16x16x32_bf16 v[22:25], v[166:169], v[206:209], v[22:25]
	v_mfma_f32_16x16x32_bf16 v[14:17], v[174:177], v[206:209], v[14:17]
	v_mfma_f32_16x16x32_bf16 v[6:9], v[166:169], v[214:217], v[6:9]
	v_mfma_f32_16x16x32_bf16 v[2:5], v[174:177], v[214:217], v[2:5]
	v_mfma_f32_16x16x32_bf16 v[54:57], v[170:173], v[186:189], v[54:57]
	v_mfma_f32_16x16x32_bf16 v[46:49], v[178:181], v[186:189], v[46:49]
	v_mfma_f32_16x16x32_bf16 v[38:41], v[170:173], v[202:205], v[38:41]
	v_mfma_f32_16x16x32_bf16 v[30:33], v[178:181], v[202:205], v[30:33]
	v_mfma_f32_16x16x32_bf16 v[22:25], v[170:173], v[210:213], v[22:25]
	v_mfma_f32_16x16x32_bf16 v[14:17], v[178:181], v[210:213], v[14:17]
	v_mfma_f32_16x16x32_bf16 v[6:9], v[170:173], v[218:221], v[6:9]
	v_mfma_f32_16x16x32_bf16 v[2:5], v[178:181], v[218:221], v[2:5]
	s_barrier
	s_setprio 0
	s_add_i32 s53, 0, 0x18000
	v_add_u32_e32 v142, s53, v147
	s_add_i32 s67, 0, 0x1c000
	ds_read_b128 v[150:153], v142
	ds_read_b128 v[154:157], v142 offset:1024
	ds_read_b128 v[158:161], v142 offset:2048
	ds_read_b128 v[162:165], v142 offset:3072
	v_add_u32_e32 v142, s67, v147
	ds_read_b128 v[166:169], v142
	ds_read_b128 v[170:173], v142 offset:1024
	ds_read_b128 v[174:177], v142 offset:2048
	ds_read_b128 v[178:181], v142 offset:3072
	s_add_u32 s54, s54, 0x40000
	s_addc_u32 s55, s55, 0
	s_mov_b32 m0, s61
	v_lshl_add_u64 v[236:237], s[54:55], 0, v[136:137]
	ds_read_b128 v[182:185], v149 offset:32768
	ds_read_b128 v[186:189], v149 offset:33792
	ds_read_b128 v[190:193], v149 offset:34816
	ds_read_b128 v[202:205], v149 offset:35840
	ds_read_b128 v[206:209], v149 offset:36864
	ds_read_b128 v[210:213], v149 offset:37888
	ds_read_b128 v[214:217], v149 offset:38912
	ds_read_b128 v[218:221], v149 offset:39936
	global_load_lds_dwordx4 v[236:237], off
	v_lshl_add_u64 v[236:237], s[54:55], 0, v[132:133]
	s_mov_b32 m0, s62
	s_nop 0
	global_load_lds_dwordx4 v[236:237], off
	s_waitcnt vmcnt(8)
	s_waitcnt lgkmcnt(0)
	s_barrier
	s_setprio 1
	s_waitcnt lgkmcnt(0)
	v_mfma_f32_16x16x32_bf16 v[126:129], v[150:153], v[182:185], v[126:129]
	v_mfma_f32_16x16x32_bf16 v[122:125], v[158:161], v[182:185], v[122:125]
	v_mfma_f32_16x16x32_bf16 v[110:113], v[150:153], v[190:193], v[110:113]
	v_mfma_f32_16x16x32_bf16 v[106:109], v[158:161], v[190:193], v[106:109]
	v_mfma_f32_16x16x32_bf16 v[94:97], v[150:153], v[206:209], v[94:97]
	v_mfma_f32_16x16x32_bf16 v[90:93], v[158:161], v[206:209], v[90:93]
	v_mfma_f32_16x16x32_bf16 v[78:81], v[150:153], v[214:217], v[78:81]
	v_mfma_f32_16x16x32_bf16 v[74:77], v[158:161], v[214:217], v[74:77]
	v_mfma_f32_16x16x32_bf16 v[126:129], v[154:157], v[186:189], v[126:129]
	v_mfma_f32_16x16x32_bf16 v[122:125], v[162:165], v[186:189], v[122:125]
	v_mfma_f32_16x16x32_bf16 v[110:113], v[154:157], v[202:205], v[110:113]
	v_mfma_f32_16x16x32_bf16 v[106:109], v[162:165], v[202:205], v[106:109]
	v_mfma_f32_16x16x32_bf16 v[94:97], v[154:157], v[210:213], v[94:97]
	v_mfma_f32_16x16x32_bf16 v[90:93], v[162:165], v[210:213], v[90:93]
	v_mfma_f32_16x16x32_bf16 v[78:81], v[154:157], v[218:221], v[78:81]
	v_mfma_f32_16x16x32_bf16 v[74:77], v[162:165], v[218:221], v[74:77]
	v_mfma_f32_16x16x32_bf16 v[118:121], v[166:169], v[182:185], v[118:121]
	v_mfma_f32_16x16x32_bf16 v[114:117], v[174:177], v[182:185], v[114:117]
	v_mfma_f32_16x16x32_bf16 v[102:105], v[166:169], v[190:193], v[102:105]
	v_mfma_f32_16x16x32_bf16 v[98:101], v[174:177], v[190:193], v[98:101]
	v_mfma_f32_16x16x32_bf16 v[86:89], v[166:169], v[206:209], v[86:89]
	v_mfma_f32_16x16x32_bf16 v[82:85], v[174:177], v[206:209], v[82:85]
	v_mfma_f32_16x16x32_bf16 v[70:73], v[166:169], v[214:217], v[70:73]
	v_mfma_f32_16x16x32_bf16 v[66:69], v[174:177], v[214:217], v[66:69]
	v_mfma_f32_16x16x32_bf16 v[118:121], v[170:173], v[186:189], v[118:121]
	v_mfma_f32_16x16x32_bf16 v[114:117], v[178:181], v[186:189], v[114:117]
	v_mfma_f32_16x16x32_bf16 v[102:105], v[170:173], v[202:205], v[102:105]
	v_mfma_f32_16x16x32_bf16 v[98:101], v[178:181], v[202:205], v[98:101]
	v_mfma_f32_16x16x32_bf16 v[86:89], v[170:173], v[210:213], v[86:89]
	v_mfma_f32_16x16x32_bf16 v[82:85], v[178:181], v[210:213], v[82:85]
	v_mfma_f32_16x16x32_bf16 v[70:73], v[170:173], v[218:221], v[70:73]
	v_mfma_f32_16x16x32_bf16 v[66:69], v[178:181], v[218:221], v[66:69]
	s_barrier
	s_setprio 0
	s_add_i32 s53, s53, s58
	v_lshl_add_u64 v[144:145], v[144:145], 0, s[10:11]
	s_mov_b32 m0, s53
	ds_read_b128 v[182:185], v149 offset:49152
	ds_read_b128 v[186:189], v149 offset:50176
	ds_read_b128 v[190:193], v149 offset:51200
	ds_read_b128 v[202:205], v149 offset:52224
	ds_read_b128 v[206:209], v149 offset:53248
	ds_read_b128 v[210:213], v149 offset:54272
	ds_read_b128 v[214:217], v149 offset:55296
	ds_read_b128 v[218:221], v149 offset:56320
	global_load_lds_dwordx4 v[144:145], off
	s_add_i32 m0, s53, 0x2000
	s_add_u32 s14, s14, 0x40080
	v_lshl_add_u64 v[144:145], v[222:223], 0, s[10:11]
	s_addc_u32 s15, s15, 0
	s_add_i32 s53, s67, s58
	global_load_lds_dwordx4 v[144:145], off
	v_lshl_add_u64 v[144:145], s[14:15], 0, v[134:135]
	s_mov_b32 m0, s53
	s_nop 0
	global_load_lds_dwordx4 v[144:145], off
	v_lshl_add_u64 v[144:145], s[14:15], 0, v[130:131]
	s_add_i32 m0, s53, 0x2000
	s_nop 0
	global_load_lds_dwordx4 v[144:145], off
	v_lshl_add_u64 v[144:145], v[232:233], 0, s[10:11]
	s_mov_b32 m0, s65
	s_nop 0
	global_load_lds_dwordx4 v[144:145], off
	v_lshl_add_u64 v[144:145], v[234:235], 0, s[10:11]
	s_mov_b32 m0, s66
	s_nop 0
	global_load_lds_dwordx4 v[144:145], off
	s_waitcnt vmcnt(8)
	s_waitcnt lgkmcnt(0)
	s_barrier
	s_setprio 1
	s_waitcnt lgkmcnt(0)
	v_mfma_f32_16x16x32_bf16 v[62:65], v[150:153], v[182:185], v[62:65]
	v_mfma_f32_16x16x32_bf16 v[58:61], v[158:161], v[182:185], v[58:61]
	v_mfma_f32_16x16x32_bf16 v[50:53], v[150:153], v[190:193], v[50:53]
	v_mfma_f32_16x16x32_bf16 v[42:45], v[158:161], v[190:193], v[42:45]
	v_mfma_f32_16x16x32_bf16 v[34:37], v[150:153], v[206:209], v[34:37]
	v_mfma_f32_16x16x32_bf16 v[26:29], v[158:161], v[206:209], v[26:29]
	v_mfma_f32_16x16x32_bf16 v[18:21], v[150:153], v[214:217], v[18:21]
	v_mfma_f32_16x16x32_bf16 v[10:13], v[158:161], v[214:217], v[10:13]
	v_mfma_f32_16x16x32_bf16 v[62:65], v[154:157], v[186:189], v[62:65]
	v_mfma_f32_16x16x32_bf16 v[58:61], v[162:165], v[186:189], v[58:61]
	v_mfma_f32_16x16x32_bf16 v[50:53], v[154:157], v[202:205], v[50:53]
	v_mfma_f32_16x16x32_bf16 v[42:45], v[162:165], v[202:205], v[42:45]
	v_mfma_f32_16x16x32_bf16 v[34:37], v[154:157], v[210:213], v[34:37]
	v_mfma_f32_16x16x32_bf16 v[26:29], v[162:165], v[210:213], v[26:29]
	v_mfma_f32_16x16x32_bf16 v[18:21], v[154:157], v[218:221], v[18:21]
	v_mfma_f32_16x16x32_bf16 v[10:13], v[162:165], v[218:221], v[10:13]
	v_mfma_f32_16x16x32_bf16 v[54:57], v[166:169], v[182:185], v[54:57]
	v_mfma_f32_16x16x32_bf16 v[46:49], v[174:177], v[182:185], v[46:49]
	v_mfma_f32_16x16x32_bf16 v[38:41], v[166:169], v[190:193], v[38:41]
	v_mfma_f32_16x16x32_bf16 v[30:33], v[174:177], v[190:193], v[30:33]
	v_mfma_f32_16x16x32_bf16 v[22:25], v[166:169], v[206:209], v[22:25]
	v_mfma_f32_16x16x32_bf16 v[14:17], v[174:177], v[206:209], v[14:17]
	v_mfma_f32_16x16x32_bf16 v[6:9], v[166:169], v[214:217], v[6:9]
	v_mfma_f32_16x16x32_bf16 v[2:5], v[174:177], v[214:217], v[2:5]
	v_mfma_f32_16x16x32_bf16 v[54:57], v[170:173], v[186:189], v[54:57]
	v_mfma_f32_16x16x32_bf16 v[46:49], v[178:181], v[186:189], v[46:49]
	v_mfma_f32_16x16x32_bf16 v[38:41], v[170:173], v[202:205], v[38:41]
	v_mfma_f32_16x16x32_bf16 v[30:33], v[178:181], v[202:205], v[30:33]
	v_mfma_f32_16x16x32_bf16 v[22:25], v[170:173], v[210:213], v[22:25]
	v_mfma_f32_16x16x32_bf16 v[14:17], v[178:181], v[210:213], v[14:17]
	v_mfma_f32_16x16x32_bf16 v[6:9], v[170:173], v[218:221], v[6:9]
	v_mfma_f32_16x16x32_bf16 v[2:5], v[178:181], v[218:221], v[2:5]
	s_barrier
	s_setprio 0
	s_add_i32 s49, s49, 2
	s_add_u32 s37, s37, 0x100
	s_addc_u32 s47, s47, 0
	s_add_u32 s4, s4, 0x100
	s_addc_u32 s5, s5, 0
	s_cmp_gt_u32 s49, 13
	s_cbranch_scc0 .LBB0_183
	s_and_b64 vcc, exec, s[44:45]
	s_cbranch_vccz .LBB0_186
	s_barrier

.LBB0_481:
	s_add_u32 s14, s12, 0xfffc0080
	s_addc_u32 s15, s13, -1
	s_add_i32 s70, 0, 0x10000
	s_cmp_eq_u32 s53, 12
	s_cselect_b32 s59, s28, s15
	s_cselect_b32 s58, s29, s14
	s_cselect_b32 s15, s33, s51
	s_cselect_b32 s14, s36, s37
	s_add_i32 s72, 0, 0x14000
	v_add_u32_e32 v134, s70, v183
	v_add_u32_e32 v168, s72, v183
	ds_read_b128 v[114:117], v134
	ds_read_b128 v[118:121], v134 offset:1024
	ds_read_b128 v[122:125], v134 offset:2048
	ds_read_b128 v[134:137], v134 offset:3072
	ds_read_b128 v[146:149], v168
	ds_read_b128 v[150:153], v168 offset:1024
	ds_read_b128 v[164:167], v168 offset:2048
	ds_read_b128 v[168:171], v168 offset:3072
	v_lshl_add_u64 v[180:181], s[12:13], 0, v[162:163]
	s_add_i32 m0, s63, 0xc000
	ds_read_b128 v[172:175], v185
	ds_read_b128 v[176:179], v185 offset:1024
	ds_read_b128 v[186:189], v185 offset:2048
	ds_read_b128 v[190:193], v185 offset:3072
	ds_read_b128 v[202:205], v185 offset:4096
	ds_read_b128 v[206:209], v185 offset:5120
	ds_read_b128 v[210:213], v185 offset:6144
	ds_read_b128 v[214:217], v185 offset:7168
	global_load_lds_dwordx4 v[180:181], off
	v_lshl_add_u64 v[180:181], s[12:13], 0, v[160:161]
	s_add_i32 m0, s63, 0xe000
	s_nop 0
	global_load_lds_dwordx4 v[180:181], off
	s_waitcnt vmcnt(8)
	s_waitcnt lgkmcnt(0)
	s_barrier
	s_setprio 1
	s_waitcnt lgkmcnt(0)
	v_mfma_f32_16x16x32_bf16 v[142:145], v[114:117], v[172:175], v[142:145]
	v_mfma_f32_16x16x32_bf16 v[138:141], v[122:125], v[172:175], v[138:141]
	v_mfma_f32_16x16x32_bf16 v[110:113], v[114:117], v[186:189], v[110:113]
	v_mfma_f32_16x16x32_bf16 v[106:109], v[122:125], v[186:189], v[106:109]
	v_mfma_f32_16x16x32_bf16 v[94:97], v[114:117], v[202:205], v[94:97]
	v_mfma_f32_16x16x32_bf16 v[90:93], v[122:125], v[202:205], v[90:93]
	v_mfma_f32_16x16x32_bf16 v[78:81], v[114:117], v[210:213], v[78:81]
	v_mfma_f32_16x16x32_bf16 v[74:77], v[122:125], v[210:213], v[74:77]
	v_mfma_f32_16x16x32_bf16 v[142:145], v[118:121], v[176:179], v[142:145]
	v_mfma_f32_16x16x32_bf16 v[138:141], v[134:137], v[176:179], v[138:141]
	v_mfma_f32_16x16x32_bf16 v[110:113], v[118:121], v[190:193], v[110:113]
	v_mfma_f32_16x16x32_bf16 v[106:109], v[134:137], v[190:193], v[106:109]
	v_mfma_f32_16x16x32_bf16 v[94:97], v[118:121], v[206:209], v[94:97]
	v_mfma_f32_16x16x32_bf16 v[90:93], v[134:137], v[206:209], v[90:93]
	v_mfma_f32_16x16x32_bf16 v[78:81], v[118:121], v[214:217], v[78:81]
	v_mfma_f32_16x16x32_bf16 v[74:77], v[134:137], v[214:217], v[74:77]
	v_mfma_f32_16x16x32_bf16 v[130:133], v[146:149], v[172:175], v[130:133]
	v_mfma_f32_16x16x32_bf16 v[126:129], v[164:167], v[172:175], v[126:129]
	v_mfma_f32_16x16x32_bf16 v[102:105], v[146:149], v[186:189], v[102:105]
	v_mfma_f32_16x16x32_bf16 v[98:101], v[164:167], v[186:189], v[98:101]
	v_mfma_f32_16x16x32_bf16 v[86:89], v[146:149], v[202:205], v[86:89]
	v_mfma_f32_16x16x32_bf16 v[82:85], v[164:167], v[202:205], v[82:85]
	v_mfma_f32_16x16x32_bf16 v[70:73], v[146:149], v[210:213], v[70:73]
	v_mfma_f32_16x16x32_bf16 v[66:69], v[164:167], v[210:213], v[66:69]
	v_mfma_f32_16x16x32_bf16 v[130:133], v[150:153], v[176:179], v[130:133]
	v_mfma_f32_16x16x32_bf16 v[126:129], v[168:171], v[176:179], v[126:129]
	v_mfma_f32_16x16x32_bf16 v[102:105], v[150:153], v[190:193], v[102:105]
	v_mfma_f32_16x16x32_bf16 v[98:101], v[168:171], v[190:193], v[98:101]
	v_mfma_f32_16x16x32_bf16 v[86:89], v[150:153], v[206:209], v[86:89]
	v_mfma_f32_16x16x32_bf16 v[82:85], v[168:171], v[206:209], v[82:85]
	v_mfma_f32_16x16x32_bf16 v[70:73], v[150:153], v[214:217], v[70:73]
	v_mfma_f32_16x16x32_bf16 v[66:69], v[168:171], v[214:217], v[66:69]
	s_barrier
	s_setprio 0
	s_add_i32 s70, s70, s62
	v_lshl_add_u64 v[180:181], s[14:15], 0, v[0:1]
	s_mov_b32 m0, s70
	ds_read_b128 v[172:175], v185 offset:16384
	ds_read_b128 v[176:179], v185 offset:17408
	ds_read_b128 v[186:189], v185 offset:18432
	ds_read_b128 v[190:193], v185 offset:19456
	ds_read_b128 v[202:205], v185 offset:20480
	ds_read_b128 v[206:209], v185 offset:21504
	ds_read_b128 v[210:213], v185 offset:22528
	ds_read_b128 v[214:217], v185 offset:23552
	global_load_lds_dwordx4 v[180:181], off
	s_add_i32 m0, s70, 0x2000
	s_add_u32 s70, s14, 0x40000
	v_lshl_add_u64 v[218:219], s[14:15], 0, v[154:155]
	s_addc_u32 s71, s15, 0
	s_add_i32 s72, s72, s62
	global_load_lds_dwordx4 v[218:219], off
	v_lshl_add_u64 v[220:221], s[70:71], 0, v[0:1]
	s_mov_b32 m0, s72
	v_lshl_add_u64 v[222:223], s[58:59], 0, v[156:157]
	global_load_lds_dwordx4 v[220:221], off
	v_lshl_add_u64 v[220:221], s[70:71], 0, v[154:155]
	s_add_i32 m0, s72, 0x2000
	s_nop 0
	global_load_lds_dwordx4 v[220:221], off
	v_lshl_add_u64 v[220:221], s[58:59], 0, v[158:159]
	s_mov_b32 m0, s63
	s_nop 0
	global_load_lds_dwordx4 v[220:221], off
	s_mov_b32 m0, s64
	s_nop 0
	global_load_lds_dwordx4 v[222:223], off
	s_waitcnt vmcnt(8)
	s_waitcnt lgkmcnt(0)
	s_barrier
	s_setprio 1
	s_waitcnt lgkmcnt(0)
	v_mfma_f32_16x16x32_bf16 v[62:65], v[114:117], v[172:175], v[62:65]
	v_mfma_f32_16x16x32_bf16 v[58:61], v[122:125], v[172:175], v[58:61]
	v_mfma_f32_16x16x32_bf16 v[46:49], v[114:117], v[186:189], v[46:49]
	v_mfma_f32_16x16x32_bf16 v[42:45], v[122:125], v[186:189], v[42:45]
	v_mfma_f32_16x16x32_bf16 v[30:33], v[114:117], v[202:205], v[30:33]
	v_mfma_f32_16x16x32_bf16 v[26:29], v[122:125], v[202:205], v[26:29]
	v_mfma_f32_16x16x32_bf16 v[14:17], v[114:117], v[210:213], v[14:17]
	v_mfma_f32_16x16x32_bf16 v[10:13], v[122:125], v[210:213], v[10:13]
	v_mfma_f32_16x16x32_bf16 v[62:65], v[118:121], v[176:179], v[62:65]
	v_mfma_f32_16x16x32_bf16 v[58:61], v[134:137], v[176:179], v[58:61]
	v_mfma_f32_16x16x32_bf16 v[46:49], v[118:121], v[190:193], v[46:49]
	v_mfma_f32_16x16x32_bf16 v[42:45], v[134:137], v[190:193], v[42:45]
	v_mfma_f32_16x16x32_bf16 v[30:33], v[118:121], v[206:209], v[30:33]
	v_mfma_f32_16x16x32_bf16 v[26:29], v[134:137], v[206:209], v[26:29]
	v_mfma_f32_16x16x32_bf16 v[14:17], v[118:121], v[214:217], v[14:17]
	v_mfma_f32_16x16x32_bf16 v[10:13], v[134:137], v[214:217], v[10:13]
	v_mfma_f32_16x16x32_bf16 v[54:57], v[146:149], v[172:175], v[54:57]
	v_mfma_f32_16x16x32_bf16 v[50:53], v[164:167], v[172:175], v[50:53]
	v_mfma_f32_16x16x32_bf16 v[38:41], v[146:149], v[186:189], v[38:41]
	v_mfma_f32_16x16x32_bf16 v[34:37], v[164:167], v[186:189], v[34:37]
	v_mfma_f32_16x16x32_bf16 v[22:25], v[146:149], v[202:205], v[22:25]
	v_mfma_f32_16x16x32_bf16 v[18:21], v[164:167], v[202:205], v[18:21]
	v_mfma_f32_16x16x32_bf16 v[6:9], v[146:149], v[210:213], v[6:9]
	v_mfma_f32_16x16x32_bf16 v[2:5], v[164:167], v[210:213], v[2:5]
	v_mfma_f32_16x16x32_bf16 v[54:57], v[150:153], v[176:179], v[54:57]
	v_mfma_f32_16x16x32_bf16 v[50:53], v[168:171], v[176:179], v[50:53]
	v_mfma_f32_16x16x32_bf16 v[38:41], v[150:153], v[190:193], v[38:41]
	v_mfma_f32_16x16x32_bf16 v[34:37], v[168:171], v[190:193], v[34:37]
	v_mfma_f32_16x16x32_bf16 v[22:25], v[150:153], v[206:209], v[22:25]
	v_mfma_f32_16x16x32_bf16 v[18:21], v[168:171], v[206:209], v[18:21]
	v_mfma_f32_16x16x32_bf16 v[6:9], v[150:153], v[214:217], v[6:9]
	v_mfma_f32_16x16x32_bf16 v[2:5], v[168:171], v[214:217], v[2:5]
	s_barrier
	s_setprio 0
	s_add_i32 s70, 0, 0x18000
	s_add_i32 s71, 0, 0x1c000
	v_add_u32_e32 v134, s70, v183
	v_add_u32_e32 v168, s71, v183
	ds_read_b128 v[114:117], v134
	ds_read_b128 v[118:121], v134 offset:1024
	ds_read_b128 v[122:125], v134 offset:2048
	ds_read_b128 v[134:137], v134 offset:3072
	ds_read_b128 v[146:149], v168
	ds_read_b128 v[150:153], v168 offset:1024
	ds_read_b128 v[164:167], v168 offset:2048
	ds_read_b128 v[168:171], v168 offset:3072
	s_add_u32 s58, s58, 0x40000
	s_addc_u32 s59, s59, 0
	s_mov_b32 m0, s65
	v_lshl_add_u64 v[232:233], s[58:59], 0, v[158:159]
	ds_read_b128 v[172:175], v185 offset:32768
	ds_read_b128 v[176:179], v185 offset:33792
	ds_read_b128 v[186:189], v185 offset:34816
	ds_read_b128 v[190:193], v185 offset:35840
	ds_read_b128 v[202:205], v185 offset:36864
	ds_read_b128 v[206:209], v185 offset:37888
	ds_read_b128 v[210:213], v185 offset:38912
	ds_read_b128 v[214:217], v185 offset:39936
	global_load_lds_dwordx4 v[232:233], off
	v_lshl_add_u64 v[232:233], s[58:59], 0, v[156:157]
	s_mov_b32 m0, s66
	s_nop 0
	global_load_lds_dwordx4 v[232:233], off
	s_waitcnt vmcnt(8)
	s_waitcnt lgkmcnt(0)
	s_barrier
	s_setprio 1
	s_waitcnt lgkmcnt(0)
	v_mfma_f32_16x16x32_bf16 v[142:145], v[114:117], v[172:175], v[142:145]
	v_mfma_f32_16x16x32_bf16 v[138:141], v[122:125], v[172:175], v[138:141]
	v_mfma_f32_16x16x32_bf16 v[110:113], v[114:117], v[186:189], v[110:113]
	v_mfma_f32_16x16x32_bf16 v[106:109], v[122:125], v[186:189], v[106:109]
	v_mfma_f32_16x16x32_bf16 v[94:97], v[114:117], v[202:205], v[94:97]
	v_mfma_f32_16x16x32_bf16 v[90:93], v[122:125], v[202:205], v[90:93]
	v_mfma_f32_16x16x32_bf16 v[78:81], v[114:117], v[210:213], v[78:81]
	v_mfma_f32_16x16x32_bf16 v[74:77], v[122:125], v[210:213], v[74:77]
	v_mfma_f32_16x16x32_bf16 v[142:145], v[118:121], v[176:179], v[142:145]
	v_mfma_f32_16x16x32_bf16 v[138:141], v[134:137], v[176:179], v[138:141]
	v_mfma_f32_16x16x32_bf16 v[110:113], v[118:121], v[190:193], v[110:113]
	v_mfma_f32_16x16x32_bf16 v[106:109], v[134:137], v[190:193], v[106:109]
	v_mfma_f32_16x16x32_bf16 v[94:97], v[118:121], v[206:209], v[94:97]
	v_mfma_f32_16x16x32_bf16 v[90:93], v[134:137], v[206:209], v[90:93]
	v_mfma_f32_16x16x32_bf16 v[78:81], v[118:121], v[214:217], v[78:81]
	v_mfma_f32_16x16x32_bf16 v[74:77], v[134:137], v[214:217], v[74:77]
	v_mfma_f32_16x16x32_bf16 v[130:133], v[146:149], v[172:175], v[130:133]
	v_mfma_f32_16x16x32_bf16 v[126:129], v[164:167], v[172:175], v[126:129]
	v_mfma_f32_16x16x32_bf16 v[102:105], v[146:149], v[186:189], v[102:105]
	v_mfma_f32_16x16x32_bf16 v[98:101], v[164:167], v[186:189], v[98:101]
	v_mfma_f32_16x16x32_bf16 v[86:89], v[146:149], v[202:205], v[86:89]
	v_mfma_f32_16x16x32_bf16 v[82:85], v[164:167], v[202:205], v[82:85]
	v_mfma_f32_16x16x32_bf16 v[70:73], v[146:149], v[210:213], v[70:73]
	v_mfma_f32_16x16x32_bf16 v[66:69], v[164:167], v[210:213], v[66:69]
	v_mfma_f32_16x16x32_bf16 v[130:133], v[150:153], v[176:179], v[130:133]
	v_mfma_f32_16x16x32_bf16 v[126:129], v[168:171], v[176:179], v[126:129]
	v_mfma_f32_16x16x32_bf16 v[102:105], v[150:153], v[190:193], v[102:105]
	v_mfma_f32_16x16x32_bf16 v[98:101], v[168:171], v[190:193], v[98:101]
	v_mfma_f32_16x16x32_bf16 v[86:89], v[150:153], v[206:209], v[86:89]
	v_mfma_f32_16x16x32_bf16 v[82:85], v[168:171], v[206:209], v[82:85]
	v_mfma_f32_16x16x32_bf16 v[70:73], v[150:153], v[214:217], v[70:73]
	v_mfma_f32_16x16x32_bf16 v[66:69], v[168:171], v[214:217], v[66:69]
	s_barrier
	s_setprio 0
	s_add_i32 s58, s70, s62
	v_lshl_add_u64 v[180:181], v[180:181], 0, s[10:11]
	s_mov_b32 m0, s58
	ds_read_b128 v[172:175], v185 offset:49152
	ds_read_b128 v[176:179], v185 offset:50176
	ds_read_b128 v[186:189], v185 offset:51200
	ds_read_b128 v[190:193], v185 offset:52224
	ds_read_b128 v[202:205], v185 offset:53248
	ds_read_b128 v[206:209], v185 offset:54272
	ds_read_b128 v[210:213], v185 offset:55296
	ds_read_b128 v[214:217], v185 offset:56320
	global_load_lds_dwordx4 v[180:181], off
	s_add_i32 m0, s58, 0x2000
	s_add_u32 s14, s14, 0x40080
	v_lshl_add_u64 v[180:181], v[218:219], 0, s[10:11]
	s_addc_u32 s15, s15, 0
	s_add_i32 s58, s71, s62
	global_load_lds_dwordx4 v[180:181], off
	v_lshl_add_u64 v[180:181], s[14:15], 0, v[0:1]
	s_mov_b32 m0, s58
	s_nop 0
	global_load_lds_dwordx4 v[180:181], off
	v_lshl_add_u64 v[180:181], s[14:15], 0, v[154:155]
	s_add_i32 m0, s58, 0x2000
	s_nop 0
	global_load_lds_dwordx4 v[180:181], off
	v_lshl_add_u64 v[180:181], v[220:221], 0, s[10:11]
	s_mov_b32 m0, s67
	s_nop 0
	global_load_lds_dwordx4 v[180:181], off
	v_lshl_add_u64 v[180:181], v[222:223], 0, s[10:11]
	s_mov_b32 m0, s68
	s_nop 0
	global_load_lds_dwordx4 v[180:181], off
	s_waitcnt vmcnt(8)
	s_waitcnt lgkmcnt(0)
	s_barrier
	s_setprio 1
	s_waitcnt lgkmcnt(0)
	v_mfma_f32_16x16x32_bf16 v[62:65], v[114:117], v[172:175], v[62:65]
	v_mfma_f32_16x16x32_bf16 v[58:61], v[122:125], v[172:175], v[58:61]
	v_mfma_f32_16x16x32_bf16 v[46:49], v[114:117], v[186:189], v[46:49]
	v_mfma_f32_16x16x32_bf16 v[42:45], v[122:125], v[186:189], v[42:45]
	v_mfma_f32_16x16x32_bf16 v[30:33], v[114:117], v[202:205], v[30:33]
	v_mfma_f32_16x16x32_bf16 v[26:29], v[122:125], v[202:205], v[26:29]
	v_mfma_f32_16x16x32_bf16 v[14:17], v[114:117], v[210:213], v[14:17]
	v_mfma_f32_16x16x32_bf16 v[10:13], v[122:125], v[210:213], v[10:13]
	v_mfma_f32_16x16x32_bf16 v[62:65], v[118:121], v[176:179], v[62:65]
	v_mfma_f32_16x16x32_bf16 v[58:61], v[134:137], v[176:179], v[58:61]
	v_mfma_f32_16x16x32_bf16 v[46:49], v[118:121], v[190:193], v[46:49]
	v_mfma_f32_16x16x32_bf16 v[42:45], v[134:137], v[190:193], v[42:45]
	v_mfma_f32_16x16x32_bf16 v[30:33], v[118:121], v[206:209], v[30:33]
	v_mfma_f32_16x16x32_bf16 v[26:29], v[134:137], v[206:209], v[26:29]
	v_mfma_f32_16x16x32_bf16 v[14:17], v[118:121], v[214:217], v[14:17]
	v_mfma_f32_16x16x32_bf16 v[10:13], v[134:137], v[214:217], v[10:13]
	v_mfma_f32_16x16x32_bf16 v[54:57], v[146:149], v[172:175], v[54:57]
	v_mfma_f32_16x16x32_bf16 v[50:53], v[164:167], v[172:175], v[50:53]
	v_mfma_f32_16x16x32_bf16 v[38:41], v[146:149], v[186:189], v[38:41]
	v_mfma_f32_16x16x32_bf16 v[34:37], v[164:167], v[186:189], v[34:37]
	v_mfma_f32_16x16x32_bf16 v[22:25], v[146:149], v[202:205], v[22:25]
	v_mfma_f32_16x16x32_bf16 v[18:21], v[164:167], v[202:205], v[18:21]
	v_mfma_f32_16x16x32_bf16 v[6:9], v[146:149], v[210:213], v[6:9]
	v_mfma_f32_16x16x32_bf16 v[2:5], v[164:167], v[210:213], v[2:5]
	v_mfma_f32_16x16x32_bf16 v[54:57], v[150:153], v[176:179], v[54:57]
	v_mfma_f32_16x16x32_bf16 v[50:53], v[168:171], v[176:179], v[50:53]
	v_mfma_f32_16x16x32_bf16 v[38:41], v[150:153], v[190:193], v[38:41]
	v_mfma_f32_16x16x32_bf16 v[34:37], v[168:171], v[190:193], v[34:37]
	v_mfma_f32_16x16x32_bf16 v[22:25], v[150:153], v[206:209], v[22:25]
	v_mfma_f32_16x16x32_bf16 v[18:21], v[168:171], v[206:209], v[18:21]
	v_mfma_f32_16x16x32_bf16 v[6:9], v[150:153], v[214:217], v[6:9]
	v_mfma_f32_16x16x32_bf16 v[2:5], v[168:171], v[214:217], v[2:5]
	s_barrier
	s_setprio 0
	s_add_i32 s53, s53, 2
	s_add_u32 s37, s37, 0x100
	s_addc_u32 s51, s51, 0
	s_add_u32 s12, s12, 0x100
	s_addc_u32 s13, s13, 0
	s_cmp_gt_u32 s53, 13
	s_cbranch_scc0 .LBB0_481
	s_and_b64 vcc, exec, s[48:49]
	s_cbranch_vccz .LBB0_484
	s_barrier

.LBB0_561:
	s_add_u32 s14, s12, 0xfffc0080
	s_addc_u32 s15, s13, -1
	s_add_i32 s66, 0, 0x10000
	s_cmp_eq_u32 s49, 12
	s_cselect_b32 s55, s28, s15
	s_cselect_b32 s54, s29, s14
	v_add_u32_e32 v140, s66, v145
	s_cselect_b32 s15, s33, s47
	s_cselect_b32 s14, s36, s37
	s_add_i32 s68, 0, 0x14000
	ds_read_b128 v[150:153], v140
	ds_read_b128 v[154:157], v140 offset:1024
	ds_read_b128 v[158:161], v140 offset:2048
	ds_read_b128 v[162:165], v140 offset:3072
	v_add_u32_e32 v140, s68, v145
	ds_read_b128 v[166:169], v140
	ds_read_b128 v[170:173], v140 offset:1024
	ds_read_b128 v[174:177], v140 offset:2048
	ds_read_b128 v[178:181], v140 offset:3072
	v_lshl_add_u64 v[142:143], s[12:13], 0, v[138:139]
	s_add_i32 m0, s59, 0xc000
	ds_read_b128 v[182:185], v149
	ds_read_b128 v[186:189], v149 offset:1024
	ds_read_b128 v[190:193], v149 offset:2048
	ds_read_b128 v[202:205], v149 offset:3072
	ds_read_b128 v[206:209], v149 offset:4096
	ds_read_b128 v[210:213], v149 offset:5120
	ds_read_b128 v[214:217], v149 offset:6144
	ds_read_b128 v[218:221], v149 offset:7168
	global_load_lds_dwordx4 v[142:143], off
	v_lshl_add_u64 v[142:143], s[12:13], 0, v[136:137]
	s_add_i32 m0, s59, 0xe000
	s_nop 0
	global_load_lds_dwordx4 v[142:143], off
	s_waitcnt vmcnt(8)
	s_waitcnt lgkmcnt(0)
	s_barrier
	s_setprio 1
	s_waitcnt lgkmcnt(0)
	v_mfma_f32_16x16x32_bf16 v[126:129], v[150:153], v[182:185], v[126:129]
	v_mfma_f32_16x16x32_bf16 v[122:125], v[158:161], v[182:185], v[122:125]
	v_mfma_f32_16x16x32_bf16 v[110:113], v[150:153], v[190:193], v[110:113]
	v_mfma_f32_16x16x32_bf16 v[106:109], v[158:161], v[190:193], v[106:109]
	v_mfma_f32_16x16x32_bf16 v[94:97], v[150:153], v[206:209], v[94:97]
	v_mfma_f32_16x16x32_bf16 v[90:93], v[158:161], v[206:209], v[90:93]
	v_mfma_f32_16x16x32_bf16 v[78:81], v[150:153], v[214:217], v[78:81]
	v_mfma_f32_16x16x32_bf16 v[74:77], v[158:161], v[214:217], v[74:77]
	v_mfma_f32_16x16x32_bf16 v[126:129], v[154:157], v[186:189], v[126:129]
	v_mfma_f32_16x16x32_bf16 v[122:125], v[162:165], v[186:189], v[122:125]
	v_mfma_f32_16x16x32_bf16 v[110:113], v[154:157], v[202:205], v[110:113]
	v_mfma_f32_16x16x32_bf16 v[106:109], v[162:165], v[202:205], v[106:109]
	v_mfma_f32_16x16x32_bf16 v[94:97], v[154:157], v[210:213], v[94:97]
	v_mfma_f32_16x16x32_bf16 v[90:93], v[162:165], v[210:213], v[90:93]
	v_mfma_f32_16x16x32_bf16 v[78:81], v[154:157], v[218:221], v[78:81]
	v_mfma_f32_16x16x32_bf16 v[74:77], v[162:165], v[218:221], v[74:77]
	v_mfma_f32_16x16x32_bf16 v[118:121], v[166:169], v[182:185], v[118:121]
	v_mfma_f32_16x16x32_bf16 v[114:117], v[174:177], v[182:185], v[114:117]
	v_mfma_f32_16x16x32_bf16 v[102:105], v[166:169], v[190:193], v[102:105]
	v_mfma_f32_16x16x32_bf16 v[98:101], v[174:177], v[190:193], v[98:101]
	v_mfma_f32_16x16x32_bf16 v[86:89], v[166:169], v[206:209], v[86:89]
	v_mfma_f32_16x16x32_bf16 v[82:85], v[174:177], v[206:209], v[82:85]
	v_mfma_f32_16x16x32_bf16 v[70:73], v[166:169], v[214:217], v[70:73]
	v_mfma_f32_16x16x32_bf16 v[66:69], v[174:177], v[214:217], v[66:69]
	v_mfma_f32_16x16x32_bf16 v[118:121], v[170:173], v[186:189], v[118:121]
	v_mfma_f32_16x16x32_bf16 v[114:117], v[178:181], v[186:189], v[114:117]
	v_mfma_f32_16x16x32_bf16 v[102:105], v[170:173], v[202:205], v[102:105]
	v_mfma_f32_16x16x32_bf16 v[98:101], v[178:181], v[202:205], v[98:101]
	v_mfma_f32_16x16x32_bf16 v[86:89], v[170:173], v[210:213], v[86:89]
	v_mfma_f32_16x16x32_bf16 v[82:85], v[178:181], v[210:213], v[82:85]
	v_mfma_f32_16x16x32_bf16 v[70:73], v[170:173], v[218:221], v[70:73]
	v_mfma_f32_16x16x32_bf16 v[66:69], v[178:181], v[218:221], v[66:69]
	s_barrier
	s_setprio 0
	s_add_i32 s66, s66, s58
	v_lshl_add_u64 v[142:143], s[14:15], 0, v[0:1]
	s_mov_b32 m0, s66
	ds_read_b128 v[182:185], v149 offset:16384
	ds_read_b128 v[186:189], v149 offset:17408
	ds_read_b128 v[190:193], v149 offset:18432
	ds_read_b128 v[202:205], v149 offset:19456
	ds_read_b128 v[206:209], v149 offset:20480
	ds_read_b128 v[210:213], v149 offset:21504
	ds_read_b128 v[214:217], v149 offset:22528
	ds_read_b128 v[218:221], v149 offset:23552
	global_load_lds_dwordx4 v[142:143], off
	s_add_i32 m0, s66, 0x2000
	s_add_u32 s66, s14, 0x40000
	v_lshl_add_u64 v[222:223], s[14:15], 0, v[130:131]
	s_addc_u32 s67, s15, 0
	s_add_i32 s68, s68, s58
	global_load_lds_dwordx4 v[222:223], off
	v_lshl_add_u64 v[232:233], s[66:67], 0, v[0:1]
	s_mov_b32 m0, s68
	v_lshl_add_u64 v[234:235], s[54:55], 0, v[132:133]
	global_load_lds_dwordx4 v[232:233], off
	v_lshl_add_u64 v[232:233], s[66:67], 0, v[130:131]
	s_add_i32 m0, s68, 0x2000
	s_nop 0
	global_load_lds_dwordx4 v[232:233], off
	v_lshl_add_u64 v[232:233], s[54:55], 0, v[134:135]
	s_mov_b32 m0, s59
	s_nop 0
	global_load_lds_dwordx4 v[232:233], off
	s_mov_b32 m0, s60
	s_nop 0
	global_load_lds_dwordx4 v[234:235], off
	s_waitcnt vmcnt(8)
	s_waitcnt lgkmcnt(0)
	s_barrier
	s_setprio 1
	s_waitcnt lgkmcnt(0)
	v_mfma_f32_16x16x32_bf16 v[62:65], v[150:153], v[182:185], v[62:65]
	v_mfma_f32_16x16x32_bf16 v[58:61], v[158:161], v[182:185], v[58:61]
	v_mfma_f32_16x16x32_bf16 v[46:49], v[150:153], v[190:193], v[46:49]
	v_mfma_f32_16x16x32_bf16 v[42:45], v[158:161], v[190:193], v[42:45]
	v_mfma_f32_16x16x32_bf16 v[30:33], v[150:153], v[206:209], v[30:33]
	v_mfma_f32_16x16x32_bf16 v[26:29], v[158:161], v[206:209], v[26:29]
	v_mfma_f32_16x16x32_bf16 v[14:17], v[150:153], v[214:217], v[14:17]
	v_mfma_f32_16x16x32_bf16 v[10:13], v[158:161], v[214:217], v[10:13]
	v_mfma_f32_16x16x32_bf16 v[62:65], v[154:157], v[186:189], v[62:65]
	v_mfma_f32_16x16x32_bf16 v[58:61], v[162:165], v[186:189], v[58:61]
	v_mfma_f32_16x16x32_bf16 v[46:49], v[154:157], v[202:205], v[46:49]
	v_mfma_f32_16x16x32_bf16 v[42:45], v[162:165], v[202:205], v[42:45]
	v_mfma_f32_16x16x32_bf16 v[30:33], v[154:157], v[210:213], v[30:33]
	v_mfma_f32_16x16x32_bf16 v[26:29], v[162:165], v[210:213], v[26:29]
	v_mfma_f32_16x16x32_bf16 v[14:17], v[154:157], v[218:221], v[14:17]
	v_mfma_f32_16x16x32_bf16 v[10:13], v[162:165], v[218:221], v[10:13]
	v_mfma_f32_16x16x32_bf16 v[54:57], v[166:169], v[182:185], v[54:57]
	v_mfma_f32_16x16x32_bf16 v[50:53], v[174:177], v[182:185], v[50:53]
	v_mfma_f32_16x16x32_bf16 v[38:41], v[166:169], v[190:193], v[38:41]
	v_mfma_f32_16x16x32_bf16 v[34:37], v[174:177], v[190:193], v[34:37]
	v_mfma_f32_16x16x32_bf16 v[22:25], v[166:169], v[206:209], v[22:25]
	v_mfma_f32_16x16x32_bf16 v[18:21], v[174:177], v[206:209], v[18:21]
	v_mfma_f32_16x16x32_bf16 v[6:9], v[166:169], v[214:217], v[6:9]
	v_mfma_f32_16x16x32_bf16 v[2:5], v[174:177], v[214:217], v[2:5]
	v_mfma_f32_16x16x32_bf16 v[54:57], v[170:173], v[186:189], v[54:57]
	v_mfma_f32_16x16x32_bf16 v[50:53], v[178:181], v[186:189], v[50:53]
	v_mfma_f32_16x16x32_bf16 v[38:41], v[170:173], v[202:205], v[38:41]
	v_mfma_f32_16x16x32_bf16 v[34:37], v[178:181], v[202:205], v[34:37]
	v_mfma_f32_16x16x32_bf16 v[22:25], v[170:173], v[210:213], v[22:25]
	v_mfma_f32_16x16x32_bf16 v[18:21], v[178:181], v[210:213], v[18:21]
	v_mfma_f32_16x16x32_bf16 v[6:9], v[170:173], v[218:221], v[6:9]
	v_mfma_f32_16x16x32_bf16 v[2:5], v[178:181], v[218:221], v[2:5]
	s_barrier
	s_setprio 0
	s_add_i32 s66, 0, 0x18000
	v_add_u32_e32 v140, s66, v145
	s_add_i32 s67, 0, 0x1c000
	ds_read_b128 v[150:153], v140
	ds_read_b128 v[154:157], v140 offset:1024
	ds_read_b128 v[158:161], v140 offset:2048
	ds_read_b128 v[162:165], v140 offset:3072
	v_add_u32_e32 v140, s67, v145
	ds_read_b128 v[166:169], v140
	ds_read_b128 v[170:173], v140 offset:1024
	ds_read_b128 v[174:177], v140 offset:2048
	ds_read_b128 v[178:181], v140 offset:3072
	s_add_u32 s54, s54, 0x40000
	s_addc_u32 s55, s55, 0
	s_mov_b32 m0, s61
	v_lshl_add_u64 v[236:237], s[54:55], 0, v[134:135]
	ds_read_b128 v[182:185], v149 offset:32768
	ds_read_b128 v[186:189], v149 offset:33792
	ds_read_b128 v[190:193], v149 offset:34816
	ds_read_b128 v[202:205], v149 offset:35840
	ds_read_b128 v[206:209], v149 offset:36864
	ds_read_b128 v[210:213], v149 offset:37888
	ds_read_b128 v[214:217], v149 offset:38912
	ds_read_b128 v[218:221], v149 offset:39936
	global_load_lds_dwordx4 v[236:237], off
	v_lshl_add_u64 v[236:237], s[54:55], 0, v[132:133]
	s_mov_b32 m0, s62
	s_nop 0
	global_load_lds_dwordx4 v[236:237], off
	s_waitcnt vmcnt(8)
	s_waitcnt lgkmcnt(0)
	s_barrier
	s_setprio 1
	s_waitcnt lgkmcnt(0)
	v_mfma_f32_16x16x32_bf16 v[126:129], v[150:153], v[182:185], v[126:129]
	v_mfma_f32_16x16x32_bf16 v[122:125], v[158:161], v[182:185], v[122:125]
	v_mfma_f32_16x16x32_bf16 v[110:113], v[150:153], v[190:193], v[110:113]
	v_mfma_f32_16x16x32_bf16 v[106:109], v[158:161], v[190:193], v[106:109]
	v_mfma_f32_16x16x32_bf16 v[94:97], v[150:153], v[206:209], v[94:97]
	v_mfma_f32_16x16x32_bf16 v[90:93], v[158:161], v[206:209], v[90:93]
	v_mfma_f32_16x16x32_bf16 v[78:81], v[150:153], v[214:217], v[78:81]
	v_mfma_f32_16x16x32_bf16 v[74:77], v[158:161], v[214:217], v[74:77]
	v_mfma_f32_16x16x32_bf16 v[126:129], v[154:157], v[186:189], v[126:129]
	v_mfma_f32_16x16x32_bf16 v[122:125], v[162:165], v[186:189], v[122:125]
	v_mfma_f32_16x16x32_bf16 v[110:113], v[154:157], v[202:205], v[110:113]
	v_mfma_f32_16x16x32_bf16 v[106:109], v[162:165], v[202:205], v[106:109]
	v_mfma_f32_16x16x32_bf16 v[94:97], v[154:157], v[210:213], v[94:97]
	v_mfma_f32_16x16x32_bf16 v[90:93], v[162:165], v[210:213], v[90:93]
	v_mfma_f32_16x16x32_bf16 v[78:81], v[154:157], v[218:221], v[78:81]
	v_mfma_f32_16x16x32_bf16 v[74:77], v[162:165], v[218:221], v[74:77]
	v_mfma_f32_16x16x32_bf16 v[118:121], v[166:169], v[182:185], v[118:121]
	v_mfma_f32_16x16x32_bf16 v[114:117], v[174:177], v[182:185], v[114:117]
	v_mfma_f32_16x16x32_bf16 v[102:105], v[166:169], v[190:193], v[102:105]
	v_mfma_f32_16x16x32_bf16 v[98:101], v[174:177], v[190:193], v[98:101]
	v_mfma_f32_16x16x32_bf16 v[86:89], v[166:169], v[206:209], v[86:89]
	v_mfma_f32_16x16x32_bf16 v[82:85], v[174:177], v[206:209], v[82:85]
	v_mfma_f32_16x16x32_bf16 v[70:73], v[166:169], v[214:217], v[70:73]
	v_mfma_f32_16x16x32_bf16 v[66:69], v[174:177], v[214:217], v[66:69]
	v_mfma_f32_16x16x32_bf16 v[118:121], v[170:173], v[186:189], v[118:121]
	v_mfma_f32_16x16x32_bf16 v[114:117], v[178:181], v[186:189], v[114:117]
	v_mfma_f32_16x16x32_bf16 v[102:105], v[170:173], v[202:205], v[102:105]
	v_mfma_f32_16x16x32_bf16 v[98:101], v[178:181], v[202:205], v[98:101]
	v_mfma_f32_16x16x32_bf16 v[86:89], v[170:173], v[210:213], v[86:89]
	v_mfma_f32_16x16x32_bf16 v[82:85], v[178:181], v[210:213], v[82:85]
	v_mfma_f32_16x16x32_bf16 v[70:73], v[170:173], v[218:221], v[70:73]
	v_mfma_f32_16x16x32_bf16 v[66:69], v[178:181], v[218:221], v[66:69]
	s_barrier
	s_setprio 0
	s_add_i32 s54, s66, s58
	v_lshl_add_u64 v[142:143], v[142:143], 0, s[10:11]
	s_mov_b32 m0, s54
	ds_read_b128 v[182:185], v149 offset:49152
	ds_read_b128 v[186:189], v149 offset:50176
	ds_read_b128 v[190:193], v149 offset:51200
	ds_read_b128 v[202:205], v149 offset:52224
	ds_read_b128 v[206:209], v149 offset:53248
	ds_read_b128 v[210:213], v149 offset:54272
	ds_read_b128 v[214:217], v149 offset:55296
	ds_read_b128 v[218:221], v149 offset:56320
	global_load_lds_dwordx4 v[142:143], off
	s_add_i32 m0, s54, 0x2000
	s_add_u32 s14, s14, 0x40080
	v_lshl_add_u64 v[142:143], v[222:223], 0, s[10:11]
	s_addc_u32 s15, s15, 0
	s_add_i32 s54, s67, s58
	global_load_lds_dwordx4 v[142:143], off
	v_lshl_add_u64 v[142:143], s[14:15], 0, v[0:1]
	s_mov_b32 m0, s54
	s_nop 0
	global_load_lds_dwordx4 v[142:143], off
	v_lshl_add_u64 v[142:143], s[14:15], 0, v[130:131]
	s_add_i32 m0, s54, 0x2000
	s_nop 0
	global_load_lds_dwordx4 v[142:143], off
	v_lshl_add_u64 v[142:143], v[232:233], 0, s[10:11]
	s_mov_b32 m0, s63
	s_nop 0
	global_load_lds_dwordx4 v[142:143], off
	v_lshl_add_u64 v[142:143], v[234:235], 0, s[10:11]
	s_mov_b32 m0, s64
	s_nop 0
	global_load_lds_dwordx4 v[142:143], off
	s_waitcnt vmcnt(8)
	s_waitcnt lgkmcnt(0)
	s_barrier
	s_setprio 1
	s_waitcnt lgkmcnt(0)
	v_mfma_f32_16x16x32_bf16 v[62:65], v[150:153], v[182:185], v[62:65]
	v_mfma_f32_16x16x32_bf16 v[58:61], v[158:161], v[182:185], v[58:61]
	v_mfma_f32_16x16x32_bf16 v[46:49], v[150:153], v[190:193], v[46:49]
	v_mfma_f32_16x16x32_bf16 v[42:45], v[158:161], v[190:193], v[42:45]
	v_mfma_f32_16x16x32_bf16 v[30:33], v[150:153], v[206:209], v[30:33]
	v_mfma_f32_16x16x32_bf16 v[26:29], v[158:161], v[206:209], v[26:29]
	v_mfma_f32_16x16x32_bf16 v[14:17], v[150:153], v[214:217], v[14:17]
	v_mfma_f32_16x16x32_bf16 v[10:13], v[158:161], v[214:217], v[10:13]
	v_mfma_f32_16x16x32_bf16 v[62:65], v[154:157], v[186:189], v[62:65]
	v_mfma_f32_16x16x32_bf16 v[58:61], v[162:165], v[186:189], v[58:61]
	v_mfma_f32_16x16x32_bf16 v[46:49], v[154:157], v[202:205], v[46:49]
	v_mfma_f32_16x16x32_bf16 v[42:45], v[162:165], v[202:205], v[42:45]
	v_mfma_f32_16x16x32_bf16 v[30:33], v[154:157], v[210:213], v[30:33]
	v_mfma_f32_16x16x32_bf16 v[26:29], v[162:165], v[210:213], v[26:29]
	v_mfma_f32_16x16x32_bf16 v[14:17], v[154:157], v[218:221], v[14:17]
	v_mfma_f32_16x16x32_bf16 v[10:13], v[162:165], v[218:221], v[10:13]
	v_mfma_f32_16x16x32_bf16 v[54:57], v[166:169], v[182:185], v[54:57]
	v_mfma_f32_16x16x32_bf16 v[50:53], v[174:177], v[182:185], v[50:53]
	v_mfma_f32_16x16x32_bf16 v[38:41], v[166:169], v[190:193], v[38:41]
	v_mfma_f32_16x16x32_bf16 v[34:37], v[174:177], v[190:193], v[34:37]
	v_mfma_f32_16x16x32_bf16 v[22:25], v[166:169], v[206:209], v[22:25]
	v_mfma_f32_16x16x32_bf16 v[18:21], v[174:177], v[206:209], v[18:21]
	v_mfma_f32_16x16x32_bf16 v[6:9], v[166:169], v[214:217], v[6:9]
	v_mfma_f32_16x16x32_bf16 v[2:5], v[174:177], v[214:217], v[2:5]
	v_mfma_f32_16x16x32_bf16 v[54:57], v[170:173], v[186:189], v[54:57]
	v_mfma_f32_16x16x32_bf16 v[50:53], v[178:181], v[186:189], v[50:53]
	v_mfma_f32_16x16x32_bf16 v[38:41], v[170:173], v[202:205], v[38:41]
	v_mfma_f32_16x16x32_bf16 v[34:37], v[178:181], v[202:205], v[34:37]
	v_mfma_f32_16x16x32_bf16 v[22:25], v[170:173], v[210:213], v[22:25]
	v_mfma_f32_16x16x32_bf16 v[18:21], v[178:181], v[210:213], v[18:21]
	v_mfma_f32_16x16x32_bf16 v[6:9], v[170:173], v[218:221], v[6:9]
	v_mfma_f32_16x16x32_bf16 v[2:5], v[178:181], v[218:221], v[2:5]
	s_barrier
	s_setprio 0
	s_add_i32 s49, s49, 2
	s_add_u32 s37, s37, 0x100
	s_addc_u32 s47, s47, 0
	s_add_u32 s12, s12, 0x100
	s_addc_u32 s13, s13, 0
	s_cmp_gt_u32 s49, 13
	s_cbranch_scc0 .LBB0_561
	s_and_b64 vcc, exec, s[44:45]
	s_cbranch_vccz .LBB0_564
	s_barrier

.LBB0_626:
	s_add_u32 s14, s12, 0xfff00080
	s_addc_u32 s15, s13, -1
	s_add_i32 s70, 0, 0x10000
	s_cmp_eq_u32 s53, 60
	s_cselect_b32 s59, s28, s15
	s_cselect_b32 s58, s29, s14
	s_cselect_b32 s15, s33, s51
	s_cselect_b32 s14, s36, s37
	s_add_i32 s72, 0, 0x14000
	v_add_u32_e32 v134, s70, v183
	v_add_u32_e32 v168, s72, v183
	ds_read_b128 v[114:117], v134
	ds_read_b128 v[118:121], v134 offset:1024
	ds_read_b128 v[122:125], v134 offset:2048
	ds_read_b128 v[134:137], v134 offset:3072
	ds_read_b128 v[146:149], v168
	ds_read_b128 v[150:153], v168 offset:1024
	ds_read_b128 v[164:167], v168 offset:2048
	ds_read_b128 v[168:171], v168 offset:3072
	v_lshl_add_u64 v[180:181], s[12:13], 0, v[162:163]
	s_add_i32 m0, s63, 0xc000
	ds_read_b128 v[172:175], v185
	ds_read_b128 v[176:179], v185 offset:1024
	ds_read_b128 v[186:189], v185 offset:2048
	ds_read_b128 v[190:193], v185 offset:3072
	ds_read_b128 v[202:205], v185 offset:4096
	ds_read_b128 v[206:209], v185 offset:5120
	ds_read_b128 v[210:213], v185 offset:6144
	ds_read_b128 v[214:217], v185 offset:7168
	global_load_lds_dwordx4 v[180:181], off
	v_lshl_add_u64 v[180:181], s[12:13], 0, v[160:161]
	s_add_i32 m0, s63, 0xe000
	s_nop 0
	global_load_lds_dwordx4 v[180:181], off
	s_waitcnt vmcnt(8)
	s_waitcnt lgkmcnt(0)
	s_barrier
	s_setprio 1
	s_waitcnt lgkmcnt(0)
	v_mfma_f32_16x16x32_bf16 v[142:145], v[114:117], v[172:175], v[142:145]
	v_mfma_f32_16x16x32_bf16 v[138:141], v[122:125], v[172:175], v[138:141]
	v_mfma_f32_16x16x32_bf16 v[110:113], v[114:117], v[186:189], v[110:113]
	v_mfma_f32_16x16x32_bf16 v[106:109], v[122:125], v[186:189], v[106:109]
	v_mfma_f32_16x16x32_bf16 v[94:97], v[114:117], v[202:205], v[94:97]
	v_mfma_f32_16x16x32_bf16 v[90:93], v[122:125], v[202:205], v[90:93]
	v_mfma_f32_16x16x32_bf16 v[78:81], v[114:117], v[210:213], v[78:81]
	v_mfma_f32_16x16x32_bf16 v[74:77], v[122:125], v[210:213], v[74:77]
	v_mfma_f32_16x16x32_bf16 v[142:145], v[118:121], v[176:179], v[142:145]
	v_mfma_f32_16x16x32_bf16 v[138:141], v[134:137], v[176:179], v[138:141]
	v_mfma_f32_16x16x32_bf16 v[110:113], v[118:121], v[190:193], v[110:113]
	v_mfma_f32_16x16x32_bf16 v[106:109], v[134:137], v[190:193], v[106:109]
	v_mfma_f32_16x16x32_bf16 v[94:97], v[118:121], v[206:209], v[94:97]
	v_mfma_f32_16x16x32_bf16 v[90:93], v[134:137], v[206:209], v[90:93]
	v_mfma_f32_16x16x32_bf16 v[78:81], v[118:121], v[214:217], v[78:81]
	v_mfma_f32_16x16x32_bf16 v[74:77], v[134:137], v[214:217], v[74:77]
	v_mfma_f32_16x16x32_bf16 v[130:133], v[146:149], v[172:175], v[130:133]
	v_mfma_f32_16x16x32_bf16 v[126:129], v[164:167], v[172:175], v[126:129]
	v_mfma_f32_16x16x32_bf16 v[102:105], v[146:149], v[186:189], v[102:105]
	v_mfma_f32_16x16x32_bf16 v[98:101], v[164:167], v[186:189], v[98:101]
	v_mfma_f32_16x16x32_bf16 v[86:89], v[146:149], v[202:205], v[86:89]
	v_mfma_f32_16x16x32_bf16 v[82:85], v[164:167], v[202:205], v[82:85]
	v_mfma_f32_16x16x32_bf16 v[70:73], v[146:149], v[210:213], v[70:73]
	v_mfma_f32_16x16x32_bf16 v[66:69], v[164:167], v[210:213], v[66:69]
	v_mfma_f32_16x16x32_bf16 v[130:133], v[150:153], v[176:179], v[130:133]
	v_mfma_f32_16x16x32_bf16 v[126:129], v[168:171], v[176:179], v[126:129]
	v_mfma_f32_16x16x32_bf16 v[102:105], v[150:153], v[190:193], v[102:105]
	v_mfma_f32_16x16x32_bf16 v[98:101], v[168:171], v[190:193], v[98:101]
	v_mfma_f32_16x16x32_bf16 v[86:89], v[150:153], v[206:209], v[86:89]
	v_mfma_f32_16x16x32_bf16 v[82:85], v[168:171], v[206:209], v[82:85]
	v_mfma_f32_16x16x32_bf16 v[70:73], v[150:153], v[214:217], v[70:73]
	v_mfma_f32_16x16x32_bf16 v[66:69], v[168:171], v[214:217], v[66:69]
	s_barrier
	s_setprio 0
	s_add_i32 s70, s70, s62
	v_lshl_add_u64 v[180:181], s[14:15], 0, v[0:1]
	s_mov_b32 m0, s70
	ds_read_b128 v[172:175], v185 offset:16384
	ds_read_b128 v[176:179], v185 offset:17408
	ds_read_b128 v[186:189], v185 offset:18432
	ds_read_b128 v[190:193], v185 offset:19456
	ds_read_b128 v[202:205], v185 offset:20480
	ds_read_b128 v[206:209], v185 offset:21504
	ds_read_b128 v[210:213], v185 offset:22528
	ds_read_b128 v[214:217], v185 offset:23552
	global_load_lds_dwordx4 v[180:181], off
	s_add_i32 m0, s70, 0x2000
	s_add_u32 s70, s14, 0x100000
	v_lshl_add_u64 v[218:219], s[14:15], 0, v[154:155]
	s_addc_u32 s71, s15, 0
	s_add_i32 s72, s72, s62
	global_load_lds_dwordx4 v[218:219], off
	v_lshl_add_u64 v[220:221], s[70:71], 0, v[0:1]
	s_mov_b32 m0, s72
	v_lshl_add_u64 v[222:223], s[58:59], 0, v[156:157]
	global_load_lds_dwordx4 v[220:221], off
	v_lshl_add_u64 v[220:221], s[70:71], 0, v[154:155]
	s_add_i32 m0, s72, 0x2000
	s_nop 0
	global_load_lds_dwordx4 v[220:221], off
	v_lshl_add_u64 v[220:221], s[58:59], 0, v[158:159]
	s_mov_b32 m0, s63
	s_nop 0
	global_load_lds_dwordx4 v[220:221], off
	s_mov_b32 m0, s64
	s_nop 0
	global_load_lds_dwordx4 v[222:223], off
	s_waitcnt vmcnt(8)
	s_waitcnt lgkmcnt(0)
	s_barrier
	s_setprio 1
	s_waitcnt lgkmcnt(0)
	v_mfma_f32_16x16x32_bf16 v[62:65], v[114:117], v[172:175], v[62:65]
	v_mfma_f32_16x16x32_bf16 v[58:61], v[122:125], v[172:175], v[58:61]
	v_mfma_f32_16x16x32_bf16 v[46:49], v[114:117], v[186:189], v[46:49]
	v_mfma_f32_16x16x32_bf16 v[42:45], v[122:125], v[186:189], v[42:45]
	v_mfma_f32_16x16x32_bf16 v[30:33], v[114:117], v[202:205], v[30:33]
	v_mfma_f32_16x16x32_bf16 v[26:29], v[122:125], v[202:205], v[26:29]
	v_mfma_f32_16x16x32_bf16 v[14:17], v[114:117], v[210:213], v[14:17]
	v_mfma_f32_16x16x32_bf16 v[10:13], v[122:125], v[210:213], v[10:13]
	v_mfma_f32_16x16x32_bf16 v[62:65], v[118:121], v[176:179], v[62:65]
	v_mfma_f32_16x16x32_bf16 v[58:61], v[134:137], v[176:179], v[58:61]
	v_mfma_f32_16x16x32_bf16 v[46:49], v[118:121], v[190:193], v[46:49]
	v_mfma_f32_16x16x32_bf16 v[42:45], v[134:137], v[190:193], v[42:45]
	v_mfma_f32_16x16x32_bf16 v[30:33], v[118:121], v[206:209], v[30:33]
	v_mfma_f32_16x16x32_bf16 v[26:29], v[134:137], v[206:209], v[26:29]
	v_mfma_f32_16x16x32_bf16 v[14:17], v[118:121], v[214:217], v[14:17]
	v_mfma_f32_16x16x32_bf16 v[10:13], v[134:137], v[214:217], v[10:13]
	v_mfma_f32_16x16x32_bf16 v[54:57], v[146:149], v[172:175], v[54:57]
	v_mfma_f32_16x16x32_bf16 v[50:53], v[164:167], v[172:175], v[50:53]
	v_mfma_f32_16x16x32_bf16 v[38:41], v[146:149], v[186:189], v[38:41]
	v_mfma_f32_16x16x32_bf16 v[34:37], v[164:167], v[186:189], v[34:37]
	v_mfma_f32_16x16x32_bf16 v[22:25], v[146:149], v[202:205], v[22:25]
	v_mfma_f32_16x16x32_bf16 v[18:21], v[164:167], v[202:205], v[18:21]
	v_mfma_f32_16x16x32_bf16 v[6:9], v[146:149], v[210:213], v[6:9]
	v_mfma_f32_16x16x32_bf16 v[2:5], v[164:167], v[210:213], v[2:5]
	v_mfma_f32_16x16x32_bf16 v[54:57], v[150:153], v[176:179], v[54:57]
	v_mfma_f32_16x16x32_bf16 v[50:53], v[168:171], v[176:179], v[50:53]
	v_mfma_f32_16x16x32_bf16 v[38:41], v[150:153], v[190:193], v[38:41]
	v_mfma_f32_16x16x32_bf16 v[34:37], v[168:171], v[190:193], v[34:37]
	v_mfma_f32_16x16x32_bf16 v[22:25], v[150:153], v[206:209], v[22:25]
	v_mfma_f32_16x16x32_bf16 v[18:21], v[168:171], v[206:209], v[18:21]
	v_mfma_f32_16x16x32_bf16 v[6:9], v[150:153], v[214:217], v[6:9]
	v_mfma_f32_16x16x32_bf16 v[2:5], v[168:171], v[214:217], v[2:5]
	s_barrier
	s_setprio 0
	s_add_i32 s70, 0, 0x18000
	s_add_i32 s71, 0, 0x1c000
	v_add_u32_e32 v134, s70, v183
	v_add_u32_e32 v168, s71, v183
	ds_read_b128 v[114:117], v134
	ds_read_b128 v[118:121], v134 offset:1024
	ds_read_b128 v[122:125], v134 offset:2048
	ds_read_b128 v[134:137], v134 offset:3072
	ds_read_b128 v[146:149], v168
	ds_read_b128 v[150:153], v168 offset:1024
	ds_read_b128 v[164:167], v168 offset:2048
	ds_read_b128 v[168:171], v168 offset:3072
	s_add_u32 s58, s58, 0x100000
	s_addc_u32 s59, s59, 0
	s_mov_b32 m0, s65
	v_lshl_add_u64 v[232:233], s[58:59], 0, v[158:159]
	ds_read_b128 v[172:175], v185 offset:32768
	ds_read_b128 v[176:179], v185 offset:33792
	ds_read_b128 v[186:189], v185 offset:34816
	ds_read_b128 v[190:193], v185 offset:35840
	ds_read_b128 v[202:205], v185 offset:36864
	ds_read_b128 v[206:209], v185 offset:37888
	ds_read_b128 v[210:213], v185 offset:38912
	ds_read_b128 v[214:217], v185 offset:39936
	global_load_lds_dwordx4 v[232:233], off
	v_lshl_add_u64 v[232:233], s[58:59], 0, v[156:157]
	s_mov_b32 m0, s66
	s_nop 0
	global_load_lds_dwordx4 v[232:233], off
	s_waitcnt vmcnt(8)
	s_waitcnt lgkmcnt(0)
	s_barrier
	s_setprio 1
	s_waitcnt lgkmcnt(0)
	v_mfma_f32_16x16x32_bf16 v[142:145], v[114:117], v[172:175], v[142:145]
	v_mfma_f32_16x16x32_bf16 v[138:141], v[122:125], v[172:175], v[138:141]
	v_mfma_f32_16x16x32_bf16 v[110:113], v[114:117], v[186:189], v[110:113]
	v_mfma_f32_16x16x32_bf16 v[106:109], v[122:125], v[186:189], v[106:109]
	v_mfma_f32_16x16x32_bf16 v[94:97], v[114:117], v[202:205], v[94:97]
	v_mfma_f32_16x16x32_bf16 v[90:93], v[122:125], v[202:205], v[90:93]
	v_mfma_f32_16x16x32_bf16 v[78:81], v[114:117], v[210:213], v[78:81]
	v_mfma_f32_16x16x32_bf16 v[74:77], v[122:125], v[210:213], v[74:77]
	v_mfma_f32_16x16x32_bf16 v[142:145], v[118:121], v[176:179], v[142:145]
	v_mfma_f32_16x16x32_bf16 v[138:141], v[134:137], v[176:179], v[138:141]
	v_mfma_f32_16x16x32_bf16 v[110:113], v[118:121], v[190:193], v[110:113]
	v_mfma_f32_16x16x32_bf16 v[106:109], v[134:137], v[190:193], v[106:109]
	v_mfma_f32_16x16x32_bf16 v[94:97], v[118:121], v[206:209], v[94:97]
	v_mfma_f32_16x16x32_bf16 v[90:93], v[134:137], v[206:209], v[90:93]
	v_mfma_f32_16x16x32_bf16 v[78:81], v[118:121], v[214:217], v[78:81]
	v_mfma_f32_16x16x32_bf16 v[74:77], v[134:137], v[214:217], v[74:77]
	v_mfma_f32_16x16x32_bf16 v[130:133], v[146:149], v[172:175], v[130:133]
	v_mfma_f32_16x16x32_bf16 v[126:129], v[164:167], v[172:175], v[126:129]
	v_mfma_f32_16x16x32_bf16 v[102:105], v[146:149], v[186:189], v[102:105]
	v_mfma_f32_16x16x32_bf16 v[98:101], v[164:167], v[186:189], v[98:101]
	v_mfma_f32_16x16x32_bf16 v[86:89], v[146:149], v[202:205], v[86:89]
	v_mfma_f32_16x16x32_bf16 v[82:85], v[164:167], v[202:205], v[82:85]
	v_mfma_f32_16x16x32_bf16 v[70:73], v[146:149], v[210:213], v[70:73]
	v_mfma_f32_16x16x32_bf16 v[66:69], v[164:167], v[210:213], v[66:69]
	v_mfma_f32_16x16x32_bf16 v[130:133], v[150:153], v[176:179], v[130:133]
	v_mfma_f32_16x16x32_bf16 v[126:129], v[168:171], v[176:179], v[126:129]
	v_mfma_f32_16x16x32_bf16 v[102:105], v[150:153], v[190:193], v[102:105]
	v_mfma_f32_16x16x32_bf16 v[98:101], v[168:171], v[190:193], v[98:101]
	v_mfma_f32_16x16x32_bf16 v[86:89], v[150:153], v[206:209], v[86:89]
	v_mfma_f32_16x16x32_bf16 v[82:85], v[168:171], v[206:209], v[82:85]
	v_mfma_f32_16x16x32_bf16 v[70:73], v[150:153], v[214:217], v[70:73]
	v_mfma_f32_16x16x32_bf16 v[66:69], v[168:171], v[214:217], v[66:69]
	s_barrier
	s_setprio 0
	s_add_i32 s58, s70, s62
	v_lshl_add_u64 v[180:181], v[180:181], 0, s[10:11]
	s_mov_b32 m0, s58
	ds_read_b128 v[172:175], v185 offset:49152
	ds_read_b128 v[176:179], v185 offset:50176
	ds_read_b128 v[186:189], v185 offset:51200
	ds_read_b128 v[190:193], v185 offset:52224
	ds_read_b128 v[202:205], v185 offset:53248
	ds_read_b128 v[206:209], v185 offset:54272
	ds_read_b128 v[210:213], v185 offset:55296
	ds_read_b128 v[214:217], v185 offset:56320
	global_load_lds_dwordx4 v[180:181], off
	s_add_i32 m0, s58, 0x2000
	s_add_u32 s14, s14, 0x100080
	v_lshl_add_u64 v[180:181], v[218:219], 0, s[10:11]
	s_addc_u32 s15, s15, 0
	s_add_i32 s58, s71, s62
	global_load_lds_dwordx4 v[180:181], off
	v_lshl_add_u64 v[180:181], s[14:15], 0, v[0:1]
	s_mov_b32 m0, s58
	s_nop 0
	global_load_lds_dwordx4 v[180:181], off
	v_lshl_add_u64 v[180:181], s[14:15], 0, v[154:155]
	s_add_i32 m0, s58, 0x2000
	s_nop 0
	global_load_lds_dwordx4 v[180:181], off
	v_lshl_add_u64 v[180:181], v[220:221], 0, s[10:11]
	s_mov_b32 m0, s67
	s_nop 0
	global_load_lds_dwordx4 v[180:181], off
	v_lshl_add_u64 v[180:181], v[222:223], 0, s[10:11]
	s_mov_b32 m0, s68
	s_nop 0
	global_load_lds_dwordx4 v[180:181], off
	s_waitcnt vmcnt(8)
	s_waitcnt lgkmcnt(0)
	s_barrier
	s_setprio 1
	s_waitcnt lgkmcnt(0)
	v_mfma_f32_16x16x32_bf16 v[62:65], v[114:117], v[172:175], v[62:65]
	v_mfma_f32_16x16x32_bf16 v[58:61], v[122:125], v[172:175], v[58:61]
	v_mfma_f32_16x16x32_bf16 v[46:49], v[114:117], v[186:189], v[46:49]
	v_mfma_f32_16x16x32_bf16 v[42:45], v[122:125], v[186:189], v[42:45]
	v_mfma_f32_16x16x32_bf16 v[30:33], v[114:117], v[202:205], v[30:33]
	v_mfma_f32_16x16x32_bf16 v[26:29], v[122:125], v[202:205], v[26:29]
	v_mfma_f32_16x16x32_bf16 v[14:17], v[114:117], v[210:213], v[14:17]
	v_mfma_f32_16x16x32_bf16 v[10:13], v[122:125], v[210:213], v[10:13]
	v_mfma_f32_16x16x32_bf16 v[62:65], v[118:121], v[176:179], v[62:65]
	v_mfma_f32_16x16x32_bf16 v[58:61], v[134:137], v[176:179], v[58:61]
	v_mfma_f32_16x16x32_bf16 v[46:49], v[118:121], v[190:193], v[46:49]
	v_mfma_f32_16x16x32_bf16 v[42:45], v[134:137], v[190:193], v[42:45]
	v_mfma_f32_16x16x32_bf16 v[30:33], v[118:121], v[206:209], v[30:33]
	v_mfma_f32_16x16x32_bf16 v[26:29], v[134:137], v[206:209], v[26:29]
	v_mfma_f32_16x16x32_bf16 v[14:17], v[118:121], v[214:217], v[14:17]
	v_mfma_f32_16x16x32_bf16 v[10:13], v[134:137], v[214:217], v[10:13]
	v_mfma_f32_16x16x32_bf16 v[54:57], v[146:149], v[172:175], v[54:57]
	v_mfma_f32_16x16x32_bf16 v[50:53], v[164:167], v[172:175], v[50:53]
	v_mfma_f32_16x16x32_bf16 v[38:41], v[146:149], v[186:189], v[38:41]
	v_mfma_f32_16x16x32_bf16 v[34:37], v[164:167], v[186:189], v[34:37]
	v_mfma_f32_16x16x32_bf16 v[22:25], v[146:149], v[202:205], v[22:25]
	v_mfma_f32_16x16x32_bf16 v[18:21], v[164:167], v[202:205], v[18:21]
	v_mfma_f32_16x16x32_bf16 v[6:9], v[146:149], v[210:213], v[6:9]
	v_mfma_f32_16x16x32_bf16 v[2:5], v[164:167], v[210:213], v[2:5]
	v_mfma_f32_16x16x32_bf16 v[54:57], v[150:153], v[176:179], v[54:57]
	v_mfma_f32_16x16x32_bf16 v[50:53], v[168:171], v[176:179], v[50:53]
	v_mfma_f32_16x16x32_bf16 v[38:41], v[150:153], v[190:193], v[38:41]
	v_mfma_f32_16x16x32_bf16 v[34:37], v[168:171], v[190:193], v[34:37]
	v_mfma_f32_16x16x32_bf16 v[22:25], v[150:153], v[206:209], v[22:25]
	v_mfma_f32_16x16x32_bf16 v[18:21], v[168:171], v[206:209], v[18:21]
	v_mfma_f32_16x16x32_bf16 v[6:9], v[150:153], v[214:217], v[6:9]
	v_mfma_f32_16x16x32_bf16 v[2:5], v[168:171], v[214:217], v[2:5]
	s_barrier
	s_setprio 0
	s_add_i32 s53, s53, 2
	s_add_u32 s37, s37, 0x100
	s_addc_u32 s51, s51, 0
	s_add_u32 s12, s12, 0x100
	s_addc_u32 s13, s13, 0
	s_cmp_gt_u32 s53, 61
	s_cbranch_scc0 .LBB0_626
	s_and_b64 vcc, exec, s[48:49]
	s_cbranch_vccz .LBB0_629
	s_barrier

.LBB0_711:
	s_add_i32 s29, s28, 2
	s_add_u32 s33, s14, 0x80
	s_addc_u32 s54, s15, 0
	s_add_i32 s72, 0, 0x10000
	s_cmp_eq_u32 s66, s28
	s_cselect_b32 s55, s5, s54
	s_cselect_b32 s54, s4, s33
	s_cselect_b32 s71, s13, s21
	s_cselect_b32 s70, s12, s20
	s_add_i32 s28, 0, 0x14000
	v_add_u32_e32 v156, s72, v141
	v_add_u32_e32 v172, s28, v141
	ds_read_b128 v[144:147], v156
	ds_read_b128 v[148:151], v156 offset:1024
	ds_read_b128 v[152:155], v156 offset:2048
	ds_read_b128 v[156:159], v156 offset:3072
	ds_read_b128 v[160:163], v172
	ds_read_b128 v[164:167], v172 offset:1024
	ds_read_b128 v[168:171], v172 offset:2048
	ds_read_b128 v[172:175], v172 offset:3072
	v_lshl_add_u64 v[192:193], s[14:15], 0, v[138:139]
	s_add_i32 m0, s59, 0xc000
	ds_read_b128 v[176:179], v143
	ds_read_b128 v[180:183], v143 offset:1024
	ds_read_b128 v[184:187], v143 offset:2048
	ds_read_b128 v[188:191], v143 offset:3072
	ds_read_b128 v[202:205], v143 offset:4096
	ds_read_b128 v[206:209], v143 offset:5120
	ds_read_b128 v[210:213], v143 offset:6144
	ds_read_b128 v[214:217], v143 offset:7168
	global_load_lds_dwordx4 v[192:193], off
	v_lshl_add_u64 v[192:193], s[14:15], 0, v[136:137]
	s_add_i32 m0, s59, 0xe000
	s_nop 0
	global_load_lds_dwordx4 v[192:193], off
	s_waitcnt vmcnt(8)
	s_waitcnt lgkmcnt(0)
	s_barrier
	s_setprio 1
	s_waitcnt lgkmcnt(0)
	v_mfma_f32_16x16x32_bf16 v[122:125], v[144:147], v[176:179], v[122:125]
	v_mfma_f32_16x16x32_bf16 v[126:129], v[152:155], v[176:179], v[126:129]
	v_mfma_f32_16x16x32_bf16 v[110:113], v[144:147], v[184:187], v[110:113]
	v_mfma_f32_16x16x32_bf16 v[106:109], v[152:155], v[184:187], v[106:109]
	v_mfma_f32_16x16x32_bf16 v[94:97], v[144:147], v[202:205], v[94:97]
	v_mfma_f32_16x16x32_bf16 v[90:93], v[152:155], v[202:205], v[90:93]
	v_mfma_f32_16x16x32_bf16 v[78:81], v[144:147], v[210:213], v[78:81]
	v_mfma_f32_16x16x32_bf16 v[74:77], v[152:155], v[210:213], v[74:77]
	v_mfma_f32_16x16x32_bf16 v[122:125], v[148:151], v[180:183], v[122:125]
	v_mfma_f32_16x16x32_bf16 v[126:129], v[156:159], v[180:183], v[126:129]
	v_mfma_f32_16x16x32_bf16 v[110:113], v[148:151], v[188:191], v[110:113]
	v_mfma_f32_16x16x32_bf16 v[106:109], v[156:159], v[188:191], v[106:109]
	v_mfma_f32_16x16x32_bf16 v[94:97], v[148:151], v[206:209], v[94:97]
	v_mfma_f32_16x16x32_bf16 v[90:93], v[156:159], v[206:209], v[90:93]
	v_mfma_f32_16x16x32_bf16 v[78:81], v[148:151], v[214:217], v[78:81]
	v_mfma_f32_16x16x32_bf16 v[74:77], v[156:159], v[214:217], v[74:77]
	v_mfma_f32_16x16x32_bf16 v[118:121], v[160:163], v[176:179], v[118:121]
	v_mfma_f32_16x16x32_bf16 v[114:117], v[168:171], v[176:179], v[114:117]
	v_mfma_f32_16x16x32_bf16 v[102:105], v[160:163], v[184:187], v[102:105]
	v_mfma_f32_16x16x32_bf16 v[98:101], v[168:171], v[184:187], v[98:101]
	v_mfma_f32_16x16x32_bf16 v[86:89], v[160:163], v[202:205], v[86:89]
	v_mfma_f32_16x16x32_bf16 v[82:85], v[168:171], v[202:205], v[82:85]
	v_mfma_f32_16x16x32_bf16 v[70:73], v[160:163], v[210:213], v[70:73]
	v_mfma_f32_16x16x32_bf16 v[66:69], v[168:171], v[210:213], v[66:69]
	v_mfma_f32_16x16x32_bf16 v[118:121], v[164:167], v[180:183], v[118:121]
	v_mfma_f32_16x16x32_bf16 v[114:117], v[172:175], v[180:183], v[114:117]
	v_mfma_f32_16x16x32_bf16 v[102:105], v[164:167], v[188:191], v[102:105]
	v_mfma_f32_16x16x32_bf16 v[98:101], v[172:175], v[188:191], v[98:101]
	v_mfma_f32_16x16x32_bf16 v[86:89], v[164:167], v[206:209], v[86:89]
	v_mfma_f32_16x16x32_bf16 v[82:85], v[172:175], v[206:209], v[82:85]
	v_mfma_f32_16x16x32_bf16 v[70:73], v[164:167], v[214:217], v[70:73]
	v_mfma_f32_16x16x32_bf16 v[66:69], v[172:175], v[214:217], v[66:69]
	s_barrier
	s_setprio 0
	s_add_i32 s33, s72, s58
	v_lshl_add_u64 v[192:193], s[70:71], 0, v[0:1]
	s_mov_b32 m0, s33
	ds_read_b128 v[176:179], v143 offset:16384
	ds_read_b128 v[180:183], v143 offset:17408
	ds_read_b128 v[184:187], v143 offset:18432
	ds_read_b128 v[188:191], v143 offset:19456
	ds_read_b128 v[202:205], v143 offset:20480
	ds_read_b128 v[206:209], v143 offset:21504
	ds_read_b128 v[210:213], v143 offset:22528
	ds_read_b128 v[214:217], v143 offset:23552
	global_load_lds_dwordx4 v[192:193], off
	s_add_i32 m0, s33, 0x2000
	v_lshl_add_u64 v[218:219], s[70:71], 0, v[130:131]
	s_add_u32 s70, s70, s42
	s_addc_u32 s71, s71, s43
	s_add_i32 s28, s28, s58
	global_load_lds_dwordx4 v[218:219], off
	v_lshl_add_u64 v[220:221], s[70:71], 0, v[0:1]
	s_mov_b32 m0, s28
	v_lshl_add_u64 v[222:223], s[70:71], 0, v[130:131]
	global_load_lds_dwordx4 v[220:221], off
	s_add_i32 m0, s28, 0x2000
	v_lshl_add_u64 v[232:233], s[54:55], 0, v[134:135]
	global_load_lds_dwordx4 v[222:223], off
	s_mov_b32 m0, s59
	v_lshl_add_u64 v[234:235], s[54:55], 0, v[132:133]
	global_load_lds_dwordx4 v[232:233], off
	s_mov_b32 m0, s60
	s_nop 0
	global_load_lds_dwordx4 v[234:235], off
	s_waitcnt vmcnt(8)
	s_waitcnt lgkmcnt(0)
	s_barrier
	s_setprio 1
	s_waitcnt lgkmcnt(0)
	v_mfma_f32_16x16x32_bf16 v[62:65], v[144:147], v[176:179], v[62:65]
	v_mfma_f32_16x16x32_bf16 v[58:61], v[152:155], v[176:179], v[58:61]
	v_mfma_f32_16x16x32_bf16 v[46:49], v[144:147], v[184:187], v[46:49]
	v_mfma_f32_16x16x32_bf16 v[42:45], v[152:155], v[184:187], v[42:45]
	v_mfma_f32_16x16x32_bf16 v[30:33], v[144:147], v[202:205], v[30:33]
	v_mfma_f32_16x16x32_bf16 v[26:29], v[152:155], v[202:205], v[26:29]
	v_mfma_f32_16x16x32_bf16 v[14:17], v[144:147], v[210:213], v[14:17]
	v_mfma_f32_16x16x32_bf16 v[10:13], v[152:155], v[210:213], v[10:13]
	v_mfma_f32_16x16x32_bf16 v[62:65], v[148:151], v[180:183], v[62:65]
	v_mfma_f32_16x16x32_bf16 v[58:61], v[156:159], v[180:183], v[58:61]
	v_mfma_f32_16x16x32_bf16 v[46:49], v[148:151], v[188:191], v[46:49]
	v_mfma_f32_16x16x32_bf16 v[42:45], v[156:159], v[188:191], v[42:45]
	v_mfma_f32_16x16x32_bf16 v[30:33], v[148:151], v[206:209], v[30:33]
	v_mfma_f32_16x16x32_bf16 v[26:29], v[156:159], v[206:209], v[26:29]
	v_mfma_f32_16x16x32_bf16 v[14:17], v[148:151], v[214:217], v[14:17]
	v_mfma_f32_16x16x32_bf16 v[10:13], v[156:159], v[214:217], v[10:13]
	v_mfma_f32_16x16x32_bf16 v[54:57], v[160:163], v[176:179], v[54:57]
	v_mfma_f32_16x16x32_bf16 v[50:53], v[168:171], v[176:179], v[50:53]
	v_mfma_f32_16x16x32_bf16 v[38:41], v[160:163], v[184:187], v[38:41]
	v_mfma_f32_16x16x32_bf16 v[34:37], v[168:171], v[184:187], v[34:37]
	v_mfma_f32_16x16x32_bf16 v[22:25], v[160:163], v[202:205], v[22:25]
	v_mfma_f32_16x16x32_bf16 v[18:21], v[168:171], v[202:205], v[18:21]
	v_mfma_f32_16x16x32_bf16 v[6:9], v[160:163], v[210:213], v[6:9]
	v_mfma_f32_16x16x32_bf16 v[2:5], v[168:171], v[210:213], v[2:5]
	v_mfma_f32_16x16x32_bf16 v[54:57], v[164:167], v[180:183], v[54:57]
	v_mfma_f32_16x16x32_bf16 v[50:53], v[172:175], v[180:183], v[50:53]
	v_mfma_f32_16x16x32_bf16 v[38:41], v[164:167], v[188:191], v[38:41]
	v_mfma_f32_16x16x32_bf16 v[34:37], v[172:175], v[188:191], v[34:37]
	v_mfma_f32_16x16x32_bf16 v[22:25], v[164:167], v[206:209], v[22:25]
	v_mfma_f32_16x16x32_bf16 v[18:21], v[172:175], v[206:209], v[18:21]
	v_mfma_f32_16x16x32_bf16 v[6:9], v[164:167], v[214:217], v[6:9]
	v_mfma_f32_16x16x32_bf16 v[2:5], v[172:175], v[214:217], v[2:5]
	s_barrier
	s_setprio 0
	s_add_i32 s28, 0, 0x18000
	s_add_i32 s33, 0, 0x1c000
	v_add_u32_e32 v156, s28, v141
	v_add_u32_e32 v172, s33, v141
	ds_read_b128 v[144:147], v156
	ds_read_b128 v[148:151], v156 offset:1024
	ds_read_b128 v[152:155], v156 offset:2048
	ds_read_b128 v[156:159], v156 offset:3072
	ds_read_b128 v[160:163], v172
	ds_read_b128 v[164:167], v172 offset:1024
	ds_read_b128 v[168:171], v172 offset:2048
	ds_read_b128 v[172:175], v172 offset:3072
	s_add_u32 s54, s54, s42
	s_addc_u32 s55, s55, s43
	s_mov_b32 m0, s61
	v_lshl_add_u64 v[236:237], s[54:55], 0, v[134:135]
	ds_read_b128 v[176:179], v143 offset:32768
	ds_read_b128 v[180:183], v143 offset:33792
	ds_read_b128 v[184:187], v143 offset:34816
	ds_read_b128 v[188:191], v143 offset:35840
	ds_read_b128 v[202:205], v143 offset:36864
	ds_read_b128 v[206:209], v143 offset:37888
	ds_read_b128 v[210:213], v143 offset:38912
	ds_read_b128 v[214:217], v143 offset:39936
	global_load_lds_dwordx4 v[236:237], off
	v_lshl_add_u64 v[236:237], s[54:55], 0, v[132:133]
	s_mov_b32 m0, s62
	s_nop 0
	global_load_lds_dwordx4 v[236:237], off
	s_waitcnt vmcnt(8)
	s_waitcnt lgkmcnt(0)
	s_barrier
	s_setprio 1
	s_waitcnt lgkmcnt(0)
	v_mfma_f32_16x16x32_bf16 v[122:125], v[144:147], v[176:179], v[122:125]
	v_mfma_f32_16x16x32_bf16 v[126:129], v[152:155], v[176:179], v[126:129]
	v_mfma_f32_16x16x32_bf16 v[110:113], v[144:147], v[184:187], v[110:113]
	v_mfma_f32_16x16x32_bf16 v[106:109], v[152:155], v[184:187], v[106:109]
	v_mfma_f32_16x16x32_bf16 v[94:97], v[144:147], v[202:205], v[94:97]
	v_mfma_f32_16x16x32_bf16 v[90:93], v[152:155], v[202:205], v[90:93]
	v_mfma_f32_16x16x32_bf16 v[78:81], v[144:147], v[210:213], v[78:81]
	v_mfma_f32_16x16x32_bf16 v[74:77], v[152:155], v[210:213], v[74:77]
	v_mfma_f32_16x16x32_bf16 v[122:125], v[148:151], v[180:183], v[122:125]
	v_mfma_f32_16x16x32_bf16 v[126:129], v[156:159], v[180:183], v[126:129]
	v_mfma_f32_16x16x32_bf16 v[110:113], v[148:151], v[188:191], v[110:113]
	v_mfma_f32_16x16x32_bf16 v[106:109], v[156:159], v[188:191], v[106:109]
	v_mfma_f32_16x16x32_bf16 v[94:97], v[148:151], v[206:209], v[94:97]
	v_mfma_f32_16x16x32_bf16 v[90:93], v[156:159], v[206:209], v[90:93]
	v_mfma_f32_16x16x32_bf16 v[78:81], v[148:151], v[214:217], v[78:81]
	v_mfma_f32_16x16x32_bf16 v[74:77], v[156:159], v[214:217], v[74:77]
	v_mfma_f32_16x16x32_bf16 v[118:121], v[160:163], v[176:179], v[118:121]
	v_mfma_f32_16x16x32_bf16 v[114:117], v[168:171], v[176:179], v[114:117]
	v_mfma_f32_16x16x32_bf16 v[102:105], v[160:163], v[184:187], v[102:105]
	v_mfma_f32_16x16x32_bf16 v[98:101], v[168:171], v[184:187], v[98:101]
	v_mfma_f32_16x16x32_bf16 v[86:89], v[160:163], v[202:205], v[86:89]
	v_mfma_f32_16x16x32_bf16 v[82:85], v[168:171], v[202:205], v[82:85]
	v_mfma_f32_16x16x32_bf16 v[70:73], v[160:163], v[210:213], v[70:73]
	v_mfma_f32_16x16x32_bf16 v[66:69], v[168:171], v[210:213], v[66:69]
	v_mfma_f32_16x16x32_bf16 v[118:121], v[164:167], v[180:183], v[118:121]
	v_mfma_f32_16x16x32_bf16 v[114:117], v[172:175], v[180:183], v[114:117]
	v_mfma_f32_16x16x32_bf16 v[102:105], v[164:167], v[188:191], v[102:105]
	v_mfma_f32_16x16x32_bf16 v[98:101], v[172:175], v[188:191], v[98:101]
	v_mfma_f32_16x16x32_bf16 v[86:89], v[164:167], v[206:209], v[86:89]
	v_mfma_f32_16x16x32_bf16 v[82:85], v[172:175], v[206:209], v[82:85]
	v_mfma_f32_16x16x32_bf16 v[70:73], v[164:167], v[214:217], v[70:73]
	v_mfma_f32_16x16x32_bf16 v[66:69], v[172:175], v[214:217], v[66:69]
	s_barrier
	s_setprio 0
	s_add_i32 s28, s28, s58
	v_lshl_add_u64 v[192:193], v[192:193], 0, s[10:11]
	s_mov_b32 m0, s28
	ds_read_b128 v[176:179], v143 offset:49152
	ds_read_b128 v[180:183], v143 offset:50176
	ds_read_b128 v[184:187], v143 offset:51200
	ds_read_b128 v[188:191], v143 offset:52224
	ds_read_b128 v[202:205], v143 offset:53248
	ds_read_b128 v[206:209], v143 offset:54272
	ds_read_b128 v[210:213], v143 offset:55296
	ds_read_b128 v[214:217], v143 offset:56320
	global_load_lds_dwordx4 v[192:193], off
	v_lshl_add_u64 v[192:193], v[218:219], 0, s[10:11]
	s_add_i32 m0, s28, 0x2000
	s_add_i32 s28, s33, s58
	global_load_lds_dwordx4 v[192:193], off
	v_lshl_add_u64 v[192:193], v[220:221], 0, s[10:11]
	s_mov_b32 m0, s28
	s_nop 0
	global_load_lds_dwordx4 v[192:193], off
	v_lshl_add_u64 v[192:193], v[222:223], 0, s[10:11]
	s_add_i32 m0, s28, 0x2000
	s_nop 0
	global_load_lds_dwordx4 v[192:193], off
	v_lshl_add_u64 v[192:193], v[232:233], 0, s[10:11]
	s_mov_b32 m0, s64
	s_nop 0
	global_load_lds_dwordx4 v[192:193], off
	v_lshl_add_u64 v[192:193], v[234:235], 0, s[10:11]
	s_mov_b32 m0, s65
	s_nop 0
	global_load_lds_dwordx4 v[192:193], off
	s_waitcnt vmcnt(8)
	s_waitcnt lgkmcnt(0)
	s_barrier
	s_setprio 1
	s_waitcnt lgkmcnt(0)
	v_mfma_f32_16x16x32_bf16 v[62:65], v[144:147], v[176:179], v[62:65]
	v_mfma_f32_16x16x32_bf16 v[58:61], v[152:155], v[176:179], v[58:61]
	v_mfma_f32_16x16x32_bf16 v[46:49], v[144:147], v[184:187], v[46:49]
	v_mfma_f32_16x16x32_bf16 v[42:45], v[152:155], v[184:187], v[42:45]
	v_mfma_f32_16x16x32_bf16 v[30:33], v[144:147], v[202:205], v[30:33]
	v_mfma_f32_16x16x32_bf16 v[26:29], v[152:155], v[202:205], v[26:29]
	v_mfma_f32_16x16x32_bf16 v[14:17], v[144:147], v[210:213], v[14:17]
	v_mfma_f32_16x16x32_bf16 v[10:13], v[152:155], v[210:213], v[10:13]
	v_mfma_f32_16x16x32_bf16 v[62:65], v[148:151], v[180:183], v[62:65]
	v_mfma_f32_16x16x32_bf16 v[58:61], v[156:159], v[180:183], v[58:61]
	v_mfma_f32_16x16x32_bf16 v[46:49], v[148:151], v[188:191], v[46:49]
	v_mfma_f32_16x16x32_bf16 v[42:45], v[156:159], v[188:191], v[42:45]
	v_mfma_f32_16x16x32_bf16 v[30:33], v[148:151], v[206:209], v[30:33]
	v_mfma_f32_16x16x32_bf16 v[26:29], v[156:159], v[206:209], v[26:29]
	v_mfma_f32_16x16x32_bf16 v[14:17], v[148:151], v[214:217], v[14:17]
	v_mfma_f32_16x16x32_bf16 v[10:13], v[156:159], v[214:217], v[10:13]
	v_mfma_f32_16x16x32_bf16 v[54:57], v[160:163], v[176:179], v[54:57]
	v_mfma_f32_16x16x32_bf16 v[50:53], v[168:171], v[176:179], v[50:53]
	v_mfma_f32_16x16x32_bf16 v[38:41], v[160:163], v[184:187], v[38:41]
	v_mfma_f32_16x16x32_bf16 v[34:37], v[168:171], v[184:187], v[34:37]
	v_mfma_f32_16x16x32_bf16 v[22:25], v[160:163], v[202:205], v[22:25]
	v_mfma_f32_16x16x32_bf16 v[18:21], v[168:171], v[202:205], v[18:21]
	v_mfma_f32_16x16x32_bf16 v[6:9], v[160:163], v[210:213], v[6:9]
	v_mfma_f32_16x16x32_bf16 v[2:5], v[168:171], v[210:213], v[2:5]
	v_mfma_f32_16x16x32_bf16 v[54:57], v[164:167], v[180:183], v[54:57]
	v_mfma_f32_16x16x32_bf16 v[50:53], v[172:175], v[180:183], v[50:53]
	v_mfma_f32_16x16x32_bf16 v[38:41], v[164:167], v[188:191], v[38:41]
	v_mfma_f32_16x16x32_bf16 v[34:37], v[172:175], v[188:191], v[34:37]
	v_mfma_f32_16x16x32_bf16 v[22:25], v[164:167], v[206:209], v[22:25]
	v_mfma_f32_16x16x32_bf16 v[18:21], v[172:175], v[206:209], v[18:21]
	v_mfma_f32_16x16x32_bf16 v[6:9], v[164:167], v[214:217], v[6:9]
	v_mfma_f32_16x16x32_bf16 v[2:5], v[172:175], v[214:217], v[2:5]
	s_barrier
	s_setprio 0
	s_add_u32 s20, s20, 0x100
	s_addc_u32 s21, s21, 0
	s_add_u32 s14, s14, 0x100
	s_addc_u32 s15, s15, 0
	s_cmp_ge_i32 s29, s63
	s_mov_b32 s28, s29
	s_cbranch_scc0 .LBB0_711

.LBB0_731:
	s_add_u32 s37, s14, 0xfffc0080
	s_addc_u32 s51, s15, -1
	s_add_i32 s53, 0, 0x10000
	s_cmp_eq_u32 s36, 12
	s_cselect_b32 s63, s13, s51
	s_cselect_b32 s62, s20, s37
	s_cselect_b32 s61, s21, s33
	s_cselect_b32 s60, s28, s29
	s_add_i32 s37, 0, 0x14000
	v_add_u32_e32 v142, s53, v232
	v_add_u32_e32 v158, s37, v232
	ds_read_b128 v[126:129], v142
	ds_read_b128 v[134:137], v142 offset:1024
	ds_read_b128 v[138:141], v142 offset:2048
	ds_read_b128 v[142:145], v142 offset:3072
	ds_read_b128 v[146:149], v158
	ds_read_b128 v[150:153], v158 offset:1024
	ds_read_b128 v[154:157], v158 offset:2048
	ds_read_b128 v[158:161], v158 offset:3072
	v_lshl_add_u64 v[212:213], s[14:15], 0, v[210:211]
	s_add_i32 m0, s59, 0xc000
	ds_read_b128 v[162:165], v234
	ds_read_b128 v[166:169], v234 offset:1024
	ds_read_b128 v[170:173], v234 offset:2048
	ds_read_b128 v[174:177], v234 offset:3072
	ds_read_b128 v[178:181], v234 offset:4096
	ds_read_b128 v[182:185], v234 offset:5120
	ds_read_b128 v[186:189], v234 offset:6144
	ds_read_b128 v[190:193], v234 offset:7168
	global_load_lds_dwordx4 v[212:213], off
	v_lshl_add_u64 v[212:213], s[14:15], 0, v[208:209]
	s_add_i32 m0, s59, 0xe000
	s_nop 0
	global_load_lds_dwordx4 v[212:213], off
	s_waitcnt vmcnt(8)
	s_waitcnt lgkmcnt(0)
	s_barrier
	s_setprio 1
	s_waitcnt lgkmcnt(0)
	v_mfma_f32_16x16x32_bf16 v[130:133], v[126:129], v[162:165], v[130:133]
	v_mfma_f32_16x16x32_bf16 v[122:125], v[138:141], v[162:165], v[122:125]
	v_mfma_f32_16x16x32_bf16 v[110:113], v[126:129], v[170:173], v[110:113]
	v_mfma_f32_16x16x32_bf16 v[106:109], v[138:141], v[170:173], v[106:109]
	v_mfma_f32_16x16x32_bf16 v[94:97], v[126:129], v[178:181], v[94:97]
	v_mfma_f32_16x16x32_bf16 v[90:93], v[138:141], v[178:181], v[90:93]
	v_mfma_f32_16x16x32_bf16 v[78:81], v[126:129], v[186:189], v[78:81]
	v_mfma_f32_16x16x32_bf16 v[74:77], v[138:141], v[186:189], v[74:77]
	v_mfma_f32_16x16x32_bf16 v[130:133], v[134:137], v[166:169], v[130:133]
	v_mfma_f32_16x16x32_bf16 v[122:125], v[142:145], v[166:169], v[122:125]
	v_mfma_f32_16x16x32_bf16 v[110:113], v[134:137], v[174:177], v[110:113]
	v_mfma_f32_16x16x32_bf16 v[106:109], v[142:145], v[174:177], v[106:109]
	v_mfma_f32_16x16x32_bf16 v[94:97], v[134:137], v[182:185], v[94:97]
	v_mfma_f32_16x16x32_bf16 v[90:93], v[142:145], v[182:185], v[90:93]
	v_mfma_f32_16x16x32_bf16 v[78:81], v[134:137], v[190:193], v[78:81]
	v_mfma_f32_16x16x32_bf16 v[74:77], v[142:145], v[190:193], v[74:77]
	v_mfma_f32_16x16x32_bf16 v[118:121], v[146:149], v[162:165], v[118:121]
	v_mfma_f32_16x16x32_bf16 v[114:117], v[154:157], v[162:165], v[114:117]
	v_mfma_f32_16x16x32_bf16 v[102:105], v[146:149], v[170:173], v[102:105]
	v_mfma_f32_16x16x32_bf16 v[98:101], v[154:157], v[170:173], v[98:101]
	v_mfma_f32_16x16x32_bf16 v[86:89], v[146:149], v[178:181], v[86:89]
	v_mfma_f32_16x16x32_bf16 v[82:85], v[154:157], v[178:181], v[82:85]
	v_mfma_f32_16x16x32_bf16 v[70:73], v[146:149], v[186:189], v[70:73]
	v_mfma_f32_16x16x32_bf16 v[66:69], v[154:157], v[186:189], v[66:69]
	v_mfma_f32_16x16x32_bf16 v[118:121], v[150:153], v[166:169], v[118:121]
	v_mfma_f32_16x16x32_bf16 v[114:117], v[158:161], v[166:169], v[114:117]
	v_mfma_f32_16x16x32_bf16 v[102:105], v[150:153], v[174:177], v[102:105]
	v_mfma_f32_16x16x32_bf16 v[98:101], v[158:161], v[174:177], v[98:101]
	v_mfma_f32_16x16x32_bf16 v[86:89], v[150:153], v[182:185], v[86:89]
	v_mfma_f32_16x16x32_bf16 v[82:85], v[158:161], v[182:185], v[82:85]
	v_mfma_f32_16x16x32_bf16 v[70:73], v[150:153], v[190:193], v[70:73]
	v_mfma_f32_16x16x32_bf16 v[66:69], v[158:161], v[190:193], v[66:69]
	s_barrier
	s_setprio 0
	s_add_i32 s51, s53, s66
	v_lshl_add_u64 v[212:213], s[60:61], 0, v[0:1]
	s_mov_b32 m0, s51
	ds_read_b128 v[162:165], v234 offset:16384
	ds_read_b128 v[166:169], v234 offset:17408
	ds_read_b128 v[170:173], v234 offset:18432
	ds_read_b128 v[174:177], v234 offset:19456
	ds_read_b128 v[178:181], v234 offset:20480
	ds_read_b128 v[182:185], v234 offset:21504
	ds_read_b128 v[186:189], v234 offset:22528
	ds_read_b128 v[190:193], v234 offset:23552
	global_load_lds_dwordx4 v[212:213], off
	s_add_i32 m0, s51, 0x2000
	s_add_u32 s74, s60, 0x40000
	v_lshl_add_u64 v[214:215], s[60:61], 0, v[202:203]
	s_addc_u32 s75, s61, 0
	s_add_i32 s37, s37, s66
	global_load_lds_dwordx4 v[214:215], off
	v_lshl_add_u64 v[216:217], s[74:75], 0, v[0:1]
	s_mov_b32 m0, s37
	v_lshl_add_u64 v[218:219], s[62:63], 0, v[204:205]
	global_load_lds_dwordx4 v[216:217], off
	v_lshl_add_u64 v[216:217], s[74:75], 0, v[202:203]
	s_add_i32 m0, s37, 0x2000
	s_nop 0
	global_load_lds_dwordx4 v[216:217], off
	v_lshl_add_u64 v[216:217], s[62:63], 0, v[206:207]
	s_mov_b32 m0, s59
	s_nop 0
	global_load_lds_dwordx4 v[216:217], off
	s_mov_b32 m0, s67
	s_nop 0
	global_load_lds_dwordx4 v[218:219], off
	s_waitcnt vmcnt(8)
	s_waitcnt lgkmcnt(0)
	s_barrier
	s_setprio 1
	s_waitcnt lgkmcnt(0)
	v_mfma_f32_16x16x32_bf16 v[62:65], v[126:129], v[162:165], v[62:65]
	v_mfma_f32_16x16x32_bf16 v[58:61], v[138:141], v[162:165], v[58:61]
	v_mfma_f32_16x16x32_bf16 v[46:49], v[126:129], v[170:173], v[46:49]
	v_mfma_f32_16x16x32_bf16 v[42:45], v[138:141], v[170:173], v[42:45]
	v_mfma_f32_16x16x32_bf16 v[30:33], v[126:129], v[178:181], v[30:33]
	v_mfma_f32_16x16x32_bf16 v[26:29], v[138:141], v[178:181], v[26:29]
	v_mfma_f32_16x16x32_bf16 v[14:17], v[126:129], v[186:189], v[14:17]
	v_mfma_f32_16x16x32_bf16 v[10:13], v[138:141], v[186:189], v[10:13]
	v_mfma_f32_16x16x32_bf16 v[62:65], v[134:137], v[166:169], v[62:65]
	v_mfma_f32_16x16x32_bf16 v[58:61], v[142:145], v[166:169], v[58:61]
	v_mfma_f32_16x16x32_bf16 v[46:49], v[134:137], v[174:177], v[46:49]
	v_mfma_f32_16x16x32_bf16 v[42:45], v[142:145], v[174:177], v[42:45]
	v_mfma_f32_16x16x32_bf16 v[30:33], v[134:137], v[182:185], v[30:33]
	v_mfma_f32_16x16x32_bf16 v[26:29], v[142:145], v[182:185], v[26:29]
	v_mfma_f32_16x16x32_bf16 v[14:17], v[134:137], v[190:193], v[14:17]
	v_mfma_f32_16x16x32_bf16 v[10:13], v[142:145], v[190:193], v[10:13]
	v_mfma_f32_16x16x32_bf16 v[54:57], v[146:149], v[162:165], v[54:57]
	v_mfma_f32_16x16x32_bf16 v[50:53], v[154:157], v[162:165], v[50:53]
	v_mfma_f32_16x16x32_bf16 v[38:41], v[146:149], v[170:173], v[38:41]
	v_mfma_f32_16x16x32_bf16 v[34:37], v[154:157], v[170:173], v[34:37]
	v_mfma_f32_16x16x32_bf16 v[22:25], v[146:149], v[178:181], v[22:25]
	v_mfma_f32_16x16x32_bf16 v[18:21], v[154:157], v[178:181], v[18:21]
	v_mfma_f32_16x16x32_bf16 v[6:9], v[146:149], v[186:189], v[6:9]
	v_mfma_f32_16x16x32_bf16 v[2:5], v[154:157], v[186:189], v[2:5]
	v_mfma_f32_16x16x32_bf16 v[54:57], v[150:153], v[166:169], v[54:57]
	v_mfma_f32_16x16x32_bf16 v[50:53], v[158:161], v[166:169], v[50:53]
	v_mfma_f32_16x16x32_bf16 v[38:41], v[150:153], v[174:177], v[38:41]
	v_mfma_f32_16x16x32_bf16 v[34:37], v[158:161], v[174:177], v[34:37]
	v_mfma_f32_16x16x32_bf16 v[22:25], v[150:153], v[182:185], v[22:25]
	v_mfma_f32_16x16x32_bf16 v[18:21], v[158:161], v[182:185], v[18:21]
	v_mfma_f32_16x16x32_bf16 v[6:9], v[150:153], v[190:193], v[6:9]
	v_mfma_f32_16x16x32_bf16 v[2:5], v[158:161], v[190:193], v[2:5]
	s_barrier
	s_setprio 0
	s_add_i32 s37, 0, 0x18000
	s_add_i32 s51, 0, 0x1c000
	v_add_u32_e32 v142, s37, v232
	v_add_u32_e32 v158, s51, v232
	ds_read_b128 v[126:129], v142
	ds_read_b128 v[134:137], v142 offset:1024
	ds_read_b128 v[138:141], v142 offset:2048
	ds_read_b128 v[142:145], v142 offset:3072
	ds_read_b128 v[146:149], v158
	ds_read_b128 v[150:153], v158 offset:1024
	ds_read_b128 v[154:157], v158 offset:2048
	ds_read_b128 v[158:161], v158 offset:3072
	s_add_u32 s62, s62, 0x40000
	s_addc_u32 s63, s63, 0
	s_mov_b32 m0, s68
	v_lshl_add_u64 v[220:221], s[62:63], 0, v[206:207]
	ds_read_b128 v[162:165], v234 offset:32768
	ds_read_b128 v[166:169], v234 offset:33792
	ds_read_b128 v[170:173], v234 offset:34816
	ds_read_b128 v[174:177], v234 offset:35840
	ds_read_b128 v[178:181], v234 offset:36864
	ds_read_b128 v[182:185], v234 offset:37888
	ds_read_b128 v[186:189], v234 offset:38912
	ds_read_b128 v[190:193], v234 offset:39936
	global_load_lds_dwordx4 v[220:221], off
	v_lshl_add_u64 v[220:221], s[62:63], 0, v[204:205]
	s_mov_b32 m0, s69
	s_nop 0
	global_load_lds_dwordx4 v[220:221], off
	s_waitcnt vmcnt(8)
	s_waitcnt lgkmcnt(0)
	s_barrier
	s_setprio 1
	s_waitcnt lgkmcnt(0)
	v_mfma_f32_16x16x32_bf16 v[130:133], v[126:129], v[162:165], v[130:133]
	v_mfma_f32_16x16x32_bf16 v[122:125], v[138:141], v[162:165], v[122:125]
	v_mfma_f32_16x16x32_bf16 v[110:113], v[126:129], v[170:173], v[110:113]
	v_mfma_f32_16x16x32_bf16 v[106:109], v[138:141], v[170:173], v[106:109]
	v_mfma_f32_16x16x32_bf16 v[94:97], v[126:129], v[178:181], v[94:97]
	v_mfma_f32_16x16x32_bf16 v[90:93], v[138:141], v[178:181], v[90:93]
	v_mfma_f32_16x16x32_bf16 v[78:81], v[126:129], v[186:189], v[78:81]
	v_mfma_f32_16x16x32_bf16 v[74:77], v[138:141], v[186:189], v[74:77]
	v_mfma_f32_16x16x32_bf16 v[130:133], v[134:137], v[166:169], v[130:133]
	v_mfma_f32_16x16x32_bf16 v[122:125], v[142:145], v[166:169], v[122:125]
	v_mfma_f32_16x16x32_bf16 v[110:113], v[134:137], v[174:177], v[110:113]
	v_mfma_f32_16x16x32_bf16 v[106:109], v[142:145], v[174:177], v[106:109]
	v_mfma_f32_16x16x32_bf16 v[94:97], v[134:137], v[182:185], v[94:97]
	v_mfma_f32_16x16x32_bf16 v[90:93], v[142:145], v[182:185], v[90:93]
	v_mfma_f32_16x16x32_bf16 v[78:81], v[134:137], v[190:193], v[78:81]
	v_mfma_f32_16x16x32_bf16 v[74:77], v[142:145], v[190:193], v[74:77]
	v_mfma_f32_16x16x32_bf16 v[118:121], v[146:149], v[162:165], v[118:121]
	v_mfma_f32_16x16x32_bf16 v[114:117], v[154:157], v[162:165], v[114:117]
	v_mfma_f32_16x16x32_bf16 v[102:105], v[146:149], v[170:173], v[102:105]
	v_mfma_f32_16x16x32_bf16 v[98:101], v[154:157], v[170:173], v[98:101]
	v_mfma_f32_16x16x32_bf16 v[86:89], v[146:149], v[178:181], v[86:89]
	v_mfma_f32_16x16x32_bf16 v[82:85], v[154:157], v[178:181], v[82:85]
	v_mfma_f32_16x16x32_bf16 v[70:73], v[146:149], v[186:189], v[70:73]
	v_mfma_f32_16x16x32_bf16 v[66:69], v[154:157], v[186:189], v[66:69]
	v_mfma_f32_16x16x32_bf16 v[118:121], v[150:153], v[166:169], v[118:121]
	v_mfma_f32_16x16x32_bf16 v[114:117], v[158:161], v[166:169], v[114:117]
	v_mfma_f32_16x16x32_bf16 v[102:105], v[150:153], v[174:177], v[102:105]
	v_mfma_f32_16x16x32_bf16 v[98:101], v[158:161], v[174:177], v[98:101]
	v_mfma_f32_16x16x32_bf16 v[86:89], v[150:153], v[182:185], v[86:89]
	v_mfma_f32_16x16x32_bf16 v[82:85], v[158:161], v[182:185], v[82:85]
	v_mfma_f32_16x16x32_bf16 v[70:73], v[150:153], v[190:193], v[70:73]
	v_mfma_f32_16x16x32_bf16 v[66:69], v[158:161], v[190:193], v[66:69]
	s_barrier
	s_setprio 0
	s_add_i32 s37, s37, s66
	v_lshl_add_u64 v[212:213], v[212:213], 0, s[10:11]
	s_mov_b32 m0, s37
	ds_read_b128 v[162:165], v234 offset:49152
	ds_read_b128 v[166:169], v234 offset:50176
	ds_read_b128 v[170:173], v234 offset:51200
	ds_read_b128 v[174:177], v234 offset:52224
	ds_read_b128 v[178:181], v234 offset:53248
	ds_read_b128 v[182:185], v234 offset:54272
	ds_read_b128 v[186:189], v234 offset:55296
	ds_read_b128 v[190:193], v234 offset:56320
	global_load_lds_dwordx4 v[212:213], off
	s_add_i32 m0, s37, 0x2000
	s_add_u32 s60, s60, 0x40080
	v_lshl_add_u64 v[212:213], v[214:215], 0, s[10:11]
	s_addc_u32 s61, s61, 0
	s_add_i32 s37, s51, s66
	global_load_lds_dwordx4 v[212:213], off
	v_lshl_add_u64 v[212:213], s[60:61], 0, v[0:1]
	s_mov_b32 m0, s37
	s_nop 0
	global_load_lds_dwordx4 v[212:213], off
	v_lshl_add_u64 v[212:213], s[60:61], 0, v[202:203]
	s_add_i32 m0, s37, 0x2000
	s_nop 0
	global_load_lds_dwordx4 v[212:213], off
	v_lshl_add_u64 v[212:213], v[216:217], 0, s[10:11]
	s_mov_b32 m0, s70
	s_nop 0
	global_load_lds_dwordx4 v[212:213], off
	v_lshl_add_u64 v[212:213], v[218:219], 0, s[10:11]
	s_mov_b32 m0, s71
	s_nop 0
	global_load_lds_dwordx4 v[212:213], off
	s_waitcnt vmcnt(8)
	s_waitcnt lgkmcnt(0)
	s_barrier
	s_setprio 1
	s_waitcnt lgkmcnt(0)
	v_mfma_f32_16x16x32_bf16 v[62:65], v[126:129], v[162:165], v[62:65]
	v_mfma_f32_16x16x32_bf16 v[58:61], v[138:141], v[162:165], v[58:61]
	v_mfma_f32_16x16x32_bf16 v[46:49], v[126:129], v[170:173], v[46:49]
	v_mfma_f32_16x16x32_bf16 v[42:45], v[138:141], v[170:173], v[42:45]
	v_mfma_f32_16x16x32_bf16 v[30:33], v[126:129], v[178:181], v[30:33]
	v_mfma_f32_16x16x32_bf16 v[26:29], v[138:141], v[178:181], v[26:29]
	v_mfma_f32_16x16x32_bf16 v[14:17], v[126:129], v[186:189], v[14:17]
	v_mfma_f32_16x16x32_bf16 v[10:13], v[138:141], v[186:189], v[10:13]
	v_mfma_f32_16x16x32_bf16 v[62:65], v[134:137], v[166:169], v[62:65]
	v_mfma_f32_16x16x32_bf16 v[58:61], v[142:145], v[166:169], v[58:61]
	v_mfma_f32_16x16x32_bf16 v[46:49], v[134:137], v[174:177], v[46:49]
	v_mfma_f32_16x16x32_bf16 v[42:45], v[142:145], v[174:177], v[42:45]
	v_mfma_f32_16x16x32_bf16 v[30:33], v[134:137], v[182:185], v[30:33]
	v_mfma_f32_16x16x32_bf16 v[26:29], v[142:145], v[182:185], v[26:29]
	v_mfma_f32_16x16x32_bf16 v[14:17], v[134:137], v[190:193], v[14:17]
	v_mfma_f32_16x16x32_bf16 v[10:13], v[142:145], v[190:193], v[10:13]
	v_mfma_f32_16x16x32_bf16 v[54:57], v[146:149], v[162:165], v[54:57]
	v_mfma_f32_16x16x32_bf16 v[50:53], v[154:157], v[162:165], v[50:53]
	v_mfma_f32_16x16x32_bf16 v[38:41], v[146:149], v[170:173], v[38:41]
	v_mfma_f32_16x16x32_bf16 v[34:37], v[154:157], v[170:173], v[34:37]
	v_mfma_f32_16x16x32_bf16 v[22:25], v[146:149], v[178:181], v[22:25]
	v_mfma_f32_16x16x32_bf16 v[18:21], v[154:157], v[178:181], v[18:21]
	v_mfma_f32_16x16x32_bf16 v[6:9], v[146:149], v[186:189], v[6:9]
	v_mfma_f32_16x16x32_bf16 v[2:5], v[154:157], v[186:189], v[2:5]
	v_mfma_f32_16x16x32_bf16 v[54:57], v[150:153], v[166:169], v[54:57]
	v_mfma_f32_16x16x32_bf16 v[50:53], v[158:161], v[166:169], v[50:53]
	v_mfma_f32_16x16x32_bf16 v[38:41], v[150:153], v[174:177], v[38:41]
	v_mfma_f32_16x16x32_bf16 v[34:37], v[158:161], v[174:177], v[34:37]
	v_mfma_f32_16x16x32_bf16 v[22:25], v[150:153], v[182:185], v[22:25]
	v_mfma_f32_16x16x32_bf16 v[18:21], v[158:161], v[182:185], v[18:21]
	v_mfma_f32_16x16x32_bf16 v[6:9], v[150:153], v[190:193], v[6:9]
	v_mfma_f32_16x16x32_bf16 v[2:5], v[158:161], v[190:193], v[2:5]
	s_barrier
	s_setprio 0
	s_add_i32 s36, s36, 2
	s_add_u32 s29, s29, 0x100
	s_addc_u32 s33, s33, 0
	s_add_u32 s14, s14, 0x100
	s_addc_u32 s15, s15, 0
	s_cmp_gt_u32 s36, 13
	s_cbranch_scc0 .LBB0_731
	s_and_b64 vcc, exec, s[48:49]
	s_cbranch_vccz .LBB0_734
	s_barrier
